# speedup vs baseline: 1.0043x; 1.0043x over previous
; #define G_STA(bufoff, gbase, ld) G_STAGE(bufoff, gbase, RA0, RA1, ld)
; #define G_STB(bufoff, gbase, ld) G_STAGE(bufoff, gbase, RB0, RB1, ld)
; #define G_LDA(dst, b, h) do { _Pragma("unroll") for (int m = 0; m < 4; ++m) _Pragma("unroll") for (int k = 0; k < 2; ++k) dst[m][k] = *(const LAS bf16x8*)(lds + G_SA(b, h) + aoff + m * 2048 + k * 1024); } while (0)
; #define G_WAIT_V(n) asm volatile("s_waitcnt vmcnt(" #n ")" ::: "memory")
; template <bool PERM, class SchedT, class Epi>
; __device__ __forceinline__ void gemm_phase(LAS unsigned char* lds, const SchedT& S, const Epi& E) {
;     ...
;         const bool has_next = S.get(ui + 1, nxt);
;         const char* nA = has_next ? nxt.A : cA; const char* nB = has_next ? nxt.B : cB;
;         const int nlda = has_next ? nxt.lda : lda, nK = has_next ? nxt.K : K;
;         const int nt = K / BK;
;         for (int t = 0; t < nt; t += 2) {
;             const bool last = (t == nt - 2);
;             const char* a1 = cA + (size_t)(t + 1) * kstep;
;             const char* a2 = last ? nA : cA + (size_t)(t + 2) * kstep; const char* b2 = last ? nB : cB + (size_t)(t + 2) * kstep;
;             const char* a3 = a2 + kstep; const char* b3 = b2 + kstep;
;             const int wlda = last ? nlda : lda, wK = last ? nK : K;
;             G_LDB(B0, 0, 0); G_SCHED; G_LDA(At, 0, 0); G_STA(G_SA(1, 1), a1 + HSTEP(lda), lda);
;             G_WAIT_L(8); G_BAR; G_WAIT_L(0); G_MMA(0, 0, At, B0); G_BAR; G_SCHED;
;             G_LDB(B1, 0, 1); G_STB(G_SB(0, 0), b2, wK);
;             G_BAR; G_WAIT_L(0); G_MMA(0, 1, At, B1); G_BAR;
;             G_LDA(At, 0, 1); G_STA(G_SA(0, 0), a2, wlda);
;             G_BAR; G_WAIT_L(0); G_MMA(1, 0, At, B0); G_BAR; G_SCHED;
;             G_STB(G_SB(0, 1), b2 + HSTEP(wK), wK);
;             G_WAIT_V(6); G_BAR; G_MMA(1, 1, At, B1); G_BAR;
;             G_LDB(B0, 1, 0); G_SCHED; G_LDA(At, 1, 0); G_STA(G_SA(0, 1), a2 + HSTEP(wlda), wlda);
;             G_WAIT_L(8); G_BAR; G_WAIT_L(0); G_MMA(0, 0, At, B0); G_BAR; G_SCHED;
;             G_LDB(B1, 1, 1); G_STB(G_SB(1, 0), b3, wK);
;             G_BAR; G_WAIT_L(0); G_MMA(0, 1, At, B1); G_BAR;
;             G_LDA(At, 1, 1); G_STA(G_SA(1, 0), a3, wlda);
;             G_BAR; G_WAIT_L(0); G_MMA(1, 0, At, B0); G_BAR; G_SCHED;
;             G_STB(G_SB(1, 1), b3 + HSTEP(wK), wK);
;             G_WAIT_V(6); G_BAR; G_MMA(1, 1, At, B1); G_BAR;
;         }
.LBB0_44:
	s_cmp_eq_u32 s45, s47
	s_cselect_b64 s[28:29], -1, 0
	s_add_i32 s47, s47, 2
	s_add_u32 s26, s22, 0x80
	s_addc_u32 s27, s23, 0
	s_and_b64 s[24:25], s[28:29], exec
	s_cselect_b32 s25, s13, s27
	s_cselect_b32 s24, s12, s26
	s_cselect_b32 s26, s40, s20
	s_add_i32 s27, 0, 0x10000
	v_add_u32_e32 v152, s27, v194
	ds_read_b128 v[134:137], v152
	ds_read_b128 v[144:147], v152 offset:1024
	ds_read_b128 v[148:151], v152 offset:2048
	ds_read_b128 v[152:155], v152 offset:3072
	s_and_b64 s[28:29], s[28:29], exec
	s_cselect_b32 s29, s19, s46
	s_cselect_b32 s28, s18, s21
	s_cselect_b32 s72, s11, s44
	v_lshl_add_u64 v[156:157], s[22:23], 0, v[130:131]
	s_add_i32 m0, s30, 0xc000
	ds_read_b128 v[160:163], v196
	ds_read_b128 v[164:167], v196 offset:1024
	ds_read_b128 v[168:171], v196 offset:2048
	ds_read_b128 v[172:175], v196 offset:3072
	ds_read_b128 v[176:179], v196 offset:4096
	ds_read_b128 v[198:201], v196 offset:5120
	ds_read_b128 v[202:205], v196 offset:6144
	ds_read_b128 v[206:209], v196 offset:7168
	global_load_lds_dwordx4 v[156:157], off
	v_lshl_add_u64 v[156:157], s[22:23], 0, v[132:133]
	s_add_i32 m0, s30, 0xe000
	s_nop 0
	global_load_lds_dwordx4 v[156:157], off
	s_waitcnt lgkmcnt(8)
	s_barrier
	s_waitcnt lgkmcnt(0)
	s_setprio 1
	s_waitcnt lgkmcnt(0)
	v_mfma_f32_16x16x32_bf16 v[126:129], v[134:137], v[160:163], v[126:129]
	v_mfma_f32_16x16x32_bf16 v[122:125], v[148:151], v[160:163], v[122:125]
	v_mfma_f32_16x16x32_bf16 v[118:121], v[134:137], v[168:171], v[118:121]
	v_mfma_f32_16x16x32_bf16 v[114:117], v[148:151], v[168:171], v[114:117]
	v_mfma_f32_16x16x32_bf16 v[102:105], v[134:137], v[176:179], v[102:105]
	v_mfma_f32_16x16x32_bf16 v[98:101], v[148:151], v[176:179], v[98:101]
	v_mfma_f32_16x16x32_bf16 v[86:89], v[134:137], v[202:205], v[86:89]
	v_mfma_f32_16x16x32_bf16 v[82:85], v[148:151], v[202:205], v[82:85]
	v_mfma_f32_16x16x32_bf16 v[126:129], v[144:147], v[164:167], v[126:129]
	v_mfma_f32_16x16x32_bf16 v[122:125], v[152:155], v[164:167], v[122:125]
	v_mfma_f32_16x16x32_bf16 v[118:121], v[144:147], v[172:175], v[118:121]
	v_mfma_f32_16x16x32_bf16 v[114:117], v[152:155], v[172:175], v[114:117]
	v_mfma_f32_16x16x32_bf16 v[102:105], v[144:147], v[198:201], v[102:105]
	v_mfma_f32_16x16x32_bf16 v[98:101], v[152:155], v[198:201], v[98:101]
	v_mfma_f32_16x16x32_bf16 v[86:89], v[144:147], v[206:209], v[86:89]
	v_mfma_f32_16x16x32_bf16 v[82:85], v[152:155], v[206:209], v[82:85]
	s_setprio 0
	s_barrier
	s_add_i32 s50, 0, 0x14000
	v_add_u32_e32 v156, s50, v194
	s_add_i32 s27, s27, s5
	ds_read_b128 v[210:213], v156
	ds_read_b128 v[214:217], v156 offset:1024
	ds_read_b128 v[218:221], v156 offset:2048
	ds_read_b128 v[222:225], v156 offset:3072
	v_mad_u64_u32 v[156:157], s[48:49], v143, s72, v[138:139]
	s_mov_b32 m0, s27
	v_mad_u64_u32 v[230:231], s[48:49], v192, s72, v[140:141]
	global_load_lds_dwordx4 v156, s[28:29]
	s_add_i32 m0, s27, 0x2000
	v_mov_b32_e32 v157, v1
	global_load_lds_dwordx4 v230, s[28:29]
	s_barrier
	s_waitcnt lgkmcnt(0)
	v_mov_b32_e32 v231, v1
	v_lshl_add_u64 v[232:233], s[28:29], 0, v[156:157]
	v_lshl_add_u64 v[234:235], s[28:29], 0, v[230:231]
	s_setprio 1
	s_waitcnt lgkmcnt(0)
	v_mfma_f32_16x16x32_bf16 v[110:113], v[210:213], v[160:163], v[110:113]
	v_mfma_f32_16x16x32_bf16 v[106:109], v[218:221], v[160:163], v[106:109]
	v_mfma_f32_16x16x32_bf16 v[94:97], v[210:213], v[168:171], v[94:97]
	v_mfma_f32_16x16x32_bf16 v[90:93], v[218:221], v[168:171], v[90:93]
	v_mfma_f32_16x16x32_bf16 v[78:81], v[210:213], v[176:179], v[78:81]
	v_mfma_f32_16x16x32_bf16 v[74:77], v[218:221], v[176:179], v[74:77]
	v_mfma_f32_16x16x32_bf16 v[70:73], v[210:213], v[202:205], v[70:73]
	v_mfma_f32_16x16x32_bf16 v[66:69], v[218:221], v[202:205], v[66:69]
	v_mfma_f32_16x16x32_bf16 v[110:113], v[214:217], v[164:167], v[110:113]
	v_mfma_f32_16x16x32_bf16 v[106:109], v[222:225], v[164:167], v[106:109]
	v_mfma_f32_16x16x32_bf16 v[94:97], v[214:217], v[172:175], v[94:97]
	v_mfma_f32_16x16x32_bf16 v[90:93], v[222:225], v[172:175], v[90:93]
	v_mfma_f32_16x16x32_bf16 v[78:81], v[214:217], v[198:201], v[78:81]
	v_mfma_f32_16x16x32_bf16 v[74:77], v[222:225], v[198:201], v[74:77]
	v_mfma_f32_16x16x32_bf16 v[70:73], v[214:217], v[206:209], v[70:73]
	v_mfma_f32_16x16x32_bf16 v[66:69], v[222:225], v[206:209], v[66:69]
	s_setprio 0
	s_mov_b32 m0, s30
	v_mad_u64_u32 v[236:237], s[48:49], s26, v139, v[138:139]
	s_barrier
	ds_read_b128 v[160:163], v196 offset:16384
	ds_read_b128 v[164:167], v196 offset:17408
	ds_read_b128 v[168:171], v196 offset:18432
	ds_read_b128 v[172:175], v196 offset:19456
	ds_read_b128 v[176:179], v196 offset:20480
	ds_read_b128 v[198:201], v196 offset:21504
	ds_read_b128 v[202:205], v196 offset:22528
	ds_read_b128 v[206:209], v196 offset:23552
	global_load_lds_dwordx4 v236, s[24:25]
	v_mad_u64_u32 v[238:239], s[48:49], s26, v141, v[140:141]
	s_mov_b32 m0, s31
	v_mov_b32_e32 v237, v1
	global_load_lds_dwordx4 v238, s[24:25]
	s_barrier
	s_waitcnt lgkmcnt(0)
	v_mov_b32_e32 v239, v1
	v_lshl_add_u64 v[240:241], s[24:25], 0, v[236:237]
	v_lshl_add_u64 v[242:243], s[24:25], 0, v[238:239]
	s_setprio 1
	s_waitcnt lgkmcnt(0)
	v_mfma_f32_16x16x32_bf16 v[62:65], v[134:137], v[160:163], v[62:65]
	v_mfma_f32_16x16x32_bf16 v[58:61], v[148:151], v[160:163], v[58:61]
	v_mfma_f32_16x16x32_bf16 v[54:57], v[134:137], v[168:171], v[54:57]
	v_mfma_f32_16x16x32_bf16 v[50:53], v[148:151], v[168:171], v[50:53]
	v_mfma_f32_16x16x32_bf16 v[38:41], v[134:137], v[176:179], v[38:41]
	v_mfma_f32_16x16x32_bf16 v[34:37], v[148:151], v[176:179], v[34:37]
	v_mfma_f32_16x16x32_bf16 v[22:25], v[134:137], v[202:205], v[22:25]
	v_mfma_f32_16x16x32_bf16 v[18:21], v[148:151], v[202:205], v[18:21]
	v_mfma_f32_16x16x32_bf16 v[62:65], v[144:147], v[164:167], v[62:65]
	v_mfma_f32_16x16x32_bf16 v[58:61], v[152:155], v[164:167], v[58:61]
	v_mfma_f32_16x16x32_bf16 v[54:57], v[144:147], v[172:175], v[54:57]
	v_mfma_f32_16x16x32_bf16 v[50:53], v[152:155], v[172:175], v[50:53]
	v_mfma_f32_16x16x32_bf16 v[38:41], v[144:147], v[198:201], v[38:41]
	v_mfma_f32_16x16x32_bf16 v[34:37], v[152:155], v[198:201], v[34:37]
	v_mfma_f32_16x16x32_bf16 v[22:25], v[144:147], v[206:209], v[22:25]
	v_mfma_f32_16x16x32_bf16 v[18:21], v[152:155], v[206:209], v[18:21]
	s_setprio 0
	s_barrier
; #define G_STA(bufoff, gbase, ld) G_STAGE(bufoff, gbase, RA0, RA1, ld)
; #define G_STB(bufoff, gbase, ld) G_STAGE(bufoff, gbase, RB0, RB1, ld)
; #define G_LDA(dst, b, h) do { _Pragma("unroll") for (int m = 0; m < 4; ++m) _Pragma("unroll") for (int k = 0; k < 2; ++k) dst[m][k] = *(const LAS bf16x8*)(lds + G_SA(b, h) + aoff + m * 2048 + k * 1024); } while (0)
; #define G_LDB(dst, b, h) do { _Pragma("unroll") for (int n = 0; n < 2; ++n) _Pragma("unroll") for (int k = 0; k < 2; ++k) dst[n][k] = *(const LAS bf16x8*)(lds + G_SB(b, h) + boff + n * 2048 + k * 1024); } while (0)
; #define G_MMA(ai, bj, At, Bt) do { __builtin_amdgcn_s_setprio(1); _Pragma("unroll") for (int m = 0; m < 4; ++m) _Pragma("unroll") for (int n = 0; n < 2; ++n) _Pragma("unroll") for (int k = 0; k < 2; ++k) \
;         acc[ai][bj][m][n] = __builtin_amdgcn_mfma_f32_16x16x32_bf16(Bt[n][k], At[m][k], acc[ai][bj][m][n], 0, 0, 0); __builtin_amdgcn_s_setprio(0); } while (0)
; #define G_WAIT_V(n) asm volatile("s_waitcnt vmcnt(" #n ")" ::: "memory")
; #define G_WAIT_L(n) asm volatile("s_waitcnt lgkmcnt(" #n ")" ::: "memory")
; template <bool PERM, class SchedT, class Epi>
; __device__ __forceinline__ void gemm_phase(LAS unsigned char* lds, const SchedT& S, const Epi& E) {
;     ...
;             G_LDB(B0, 0, 0); G_SCHED; G_LDA(At, 0, 0); G_STA(G_SA(1, 1), a1 + HSTEP(lda), lda);
;             G_WAIT_L(8); G_BAR; G_WAIT_L(0); G_MMA(0, 0, At, B0); G_BAR; G_SCHED;
;             G_LDB(B1, 0, 1); G_STB(G_SB(0, 0), b2, wK);
;             G_BAR; G_WAIT_L(0); G_MMA(0, 1, At, B1); G_BAR;
;             G_LDA(At, 0, 1); G_STA(G_SA(0, 0), a2, wlda);
;             G_BAR; G_WAIT_L(0); G_MMA(1, 0, At, B0); G_BAR; G_SCHED;
;             G_STB(G_SB(0, 1), b2 + HSTEP(wK), wK);
;             G_WAIT_V(6); G_BAR; G_MMA(1, 1, At, B1); G_BAR;
;             G_LDB(B0, 1, 0); G_SCHED; G_LDA(At, 1, 0); G_STA(G_SA(0, 1), a2 + HSTEP(wlda), wlda);
;             G_WAIT_L(8); G_BAR; G_WAIT_L(0); G_MMA(0, 0, At, B0); G_BAR; G_SCHED;
;             G_LDB(B1, 1, 1); G_STB(G_SB(1, 0), b3, wK);
;             G_BAR; G_WAIT_L(0); G_MMA(0, 1, At, B1); G_BAR;
;             G_LDA(At, 1, 1); G_STA(G_SA(1, 0), a3, wlda);
;             G_BAR; G_WAIT_L(0); G_MMA(1, 0, At, B0); G_BAR; G_SCHED;
;             G_STB(G_SB(1, 1), b3 + HSTEP(wK), wK);
;             G_WAIT_V(6); G_BAR; G_MMA(1, 1, At, B1); G_BAR;
;         }
	s_lshl_b64 s[48:49], s[72:73], 8
	s_add_u32 s28, s28, s48
	s_addc_u32 s29, s29, s49
	s_add_i32 s27, s50, s5
	s_mov_b32 m0, s27
	s_nop 0
	global_load_lds_dwordx4 v156, s[28:29]
	s_add_i32 m0, s27, 0x2000
	v_lshl_add_u64 v[156:157], s[28:29], 0, v[156:157]
	global_load_lds_dwordx4 v230, s[28:29]
	s_waitcnt vmcnt(6)
	v_lshl_add_u64 v[230:231], s[28:29], 0, v[230:231]
	s_barrier
	s_setprio 1
	v_mfma_f32_16x16x32_bf16 v[46:49], v[210:213], v[160:163], v[46:49]
	v_mfma_f32_16x16x32_bf16 v[42:45], v[218:221], v[160:163], v[42:45]
	v_mfma_f32_16x16x32_bf16 v[30:33], v[210:213], v[168:171], v[30:33]
	v_mfma_f32_16x16x32_bf16 v[26:29], v[218:221], v[168:171], v[26:29]
	v_mfma_f32_16x16x32_bf16 v[14:17], v[210:213], v[176:179], v[14:17]
	v_mfma_f32_16x16x32_bf16 v[10:13], v[218:221], v[176:179], v[10:13]
	v_mfma_f32_16x16x32_bf16 v[6:9], v[210:213], v[202:205], v[6:9]
	v_mfma_f32_16x16x32_bf16 v[2:5], v[218:221], v[202:205], v[2:5]
	v_mfma_f32_16x16x32_bf16 v[46:49], v[214:217], v[164:167], v[46:49]
	v_mfma_f32_16x16x32_bf16 v[42:45], v[222:225], v[164:167], v[42:45]
	v_mfma_f32_16x16x32_bf16 v[30:33], v[214:217], v[172:175], v[30:33]
	v_mfma_f32_16x16x32_bf16 v[26:29], v[222:225], v[172:175], v[26:29]
	v_mfma_f32_16x16x32_bf16 v[14:17], v[214:217], v[198:201], v[14:17]
	v_mfma_f32_16x16x32_bf16 v[10:13], v[222:225], v[198:201], v[10:13]
	v_mfma_f32_16x16x32_bf16 v[6:9], v[214:217], v[206:209], v[6:9]
	v_mfma_f32_16x16x32_bf16 v[2:5], v[222:225], v[206:209], v[2:5]
	s_setprio 0
	s_add_i32 s28, 0, 0x18000
	v_add_u32_e32 v152, s28, v194
	s_barrier
	ds_read_b128 v[134:137], v152
	ds_read_b128 v[144:147], v152 offset:1024
	ds_read_b128 v[148:151], v152 offset:2048
	ds_read_b128 v[152:155], v152 offset:3072
	s_mov_b32 s27, s73
	s_lshl_b64 s[26:27], s[26:27], 8
	s_add_u32 s24, s24, s26
	s_addc_u32 s25, s25, s27
	s_mov_b32 m0, s34
	ds_read_b128 v[160:163], v196 offset:32768
	ds_read_b128 v[164:167], v196 offset:33792
	ds_read_b128 v[168:171], v196 offset:34816
	ds_read_b128 v[172:175], v196 offset:35840
	ds_read_b128 v[176:179], v196 offset:36864
	ds_read_b128 v[198:201], v196 offset:37888
	ds_read_b128 v[202:205], v196 offset:38912
	ds_read_b128 v[206:209], v196 offset:39936
	global_load_lds_dwordx4 v236, s[24:25]
	s_mov_b32 m0, s35
	s_nop 0
	global_load_lds_dwordx4 v238, s[24:25]
	s_waitcnt lgkmcnt(8)
	s_barrier
	s_waitcnt lgkmcnt(0)
	s_setprio 1
	s_waitcnt lgkmcnt(0)
	v_mfma_f32_16x16x32_bf16 v[126:129], v[134:137], v[160:163], v[126:129]
	v_mfma_f32_16x16x32_bf16 v[122:125], v[148:151], v[160:163], v[122:125]
	v_mfma_f32_16x16x32_bf16 v[118:121], v[134:137], v[168:171], v[118:121]
	v_mfma_f32_16x16x32_bf16 v[114:117], v[148:151], v[168:171], v[114:117]
	v_mfma_f32_16x16x32_bf16 v[102:105], v[134:137], v[176:179], v[102:105]
	v_mfma_f32_16x16x32_bf16 v[98:101], v[148:151], v[176:179], v[98:101]
	v_mfma_f32_16x16x32_bf16 v[86:89], v[134:137], v[202:205], v[86:89]
	v_mfma_f32_16x16x32_bf16 v[82:85], v[148:151], v[202:205], v[82:85]
	v_mfma_f32_16x16x32_bf16 v[126:129], v[144:147], v[164:167], v[126:129]
	v_mfma_f32_16x16x32_bf16 v[122:125], v[152:155], v[164:167], v[122:125]
	v_mfma_f32_16x16x32_bf16 v[118:121], v[144:147], v[172:175], v[118:121]
	v_mfma_f32_16x16x32_bf16 v[114:117], v[152:155], v[172:175], v[114:117]
	v_mfma_f32_16x16x32_bf16 v[102:105], v[144:147], v[198:201], v[102:105]
	v_mfma_f32_16x16x32_bf16 v[98:101], v[152:155], v[198:201], v[98:101]
	v_mfma_f32_16x16x32_bf16 v[86:89], v[144:147], v[206:209], v[86:89]
	v_mfma_f32_16x16x32_bf16 v[82:85], v[152:155], v[206:209], v[82:85]
	s_setprio 0
	s_barrier
	s_add_i32 s24, 0, 0x1c000
	s_add_i32 s25, s28, s5
	v_add_u32_e32 v197, s24, v194
	v_lshl_add_u64 v[232:233], v[232:233], 0, s[78:79]
	s_mov_b32 m0, s25
	ds_read_b128 v[210:213], v197
	ds_read_b128 v[214:217], v197 offset:1024
	ds_read_b128 v[218:221], v197 offset:2048
	ds_read_b128 v[222:225], v197 offset:3072
	global_load_lds_dwordx4 v[232:233], off
	v_lshl_add_u64 v[232:233], v[234:235], 0, s[78:79]
	s_add_i32 m0, s25, 0x2000
	s_nop 0
	global_load_lds_dwordx4 v[232:233], off
	s_barrier
	s_waitcnt lgkmcnt(0)
	s_setprio 1
	s_waitcnt lgkmcnt(0)
	v_mfma_f32_16x16x32_bf16 v[110:113], v[210:213], v[160:163], v[110:113]
	v_mfma_f32_16x16x32_bf16 v[106:109], v[218:221], v[160:163], v[106:109]
	v_mfma_f32_16x16x32_bf16 v[94:97], v[210:213], v[168:171], v[94:97]
	v_mfma_f32_16x16x32_bf16 v[90:93], v[218:221], v[168:171], v[90:93]
	v_mfma_f32_16x16x32_bf16 v[78:81], v[210:213], v[176:179], v[78:81]
	v_mfma_f32_16x16x32_bf16 v[74:77], v[218:221], v[176:179], v[74:77]
	v_mfma_f32_16x16x32_bf16 v[70:73], v[210:213], v[202:205], v[70:73]
	v_mfma_f32_16x16x32_bf16 v[66:69], v[218:221], v[202:205], v[66:69]
	v_mfma_f32_16x16x32_bf16 v[110:113], v[214:217], v[164:167], v[110:113]
	v_mfma_f32_16x16x32_bf16 v[106:109], v[222:225], v[164:167], v[106:109]
	v_mfma_f32_16x16x32_bf16 v[94:97], v[214:217], v[172:175], v[94:97]
	v_mfma_f32_16x16x32_bf16 v[90:93], v[222:225], v[172:175], v[90:93]
	v_mfma_f32_16x16x32_bf16 v[78:81], v[214:217], v[198:201], v[78:81]
	v_mfma_f32_16x16x32_bf16 v[74:77], v[222:225], v[198:201], v[74:77]
	v_mfma_f32_16x16x32_bf16 v[70:73], v[214:217], v[206:209], v[70:73]
	v_mfma_f32_16x16x32_bf16 v[66:69], v[222:225], v[206:209], v[66:69]
	s_setprio 0
	s_mov_b32 m0, s36
	v_lshl_add_u64 v[232:233], v[240:241], 0, s[78:79]
	s_barrier
	ds_read_b128 v[160:163], v196 offset:49152
	ds_read_b128 v[164:167], v196 offset:50176
	ds_read_b128 v[168:171], v196 offset:51200
	ds_read_b128 v[172:175], v196 offset:52224
	ds_read_b128 v[176:179], v196 offset:53248
	ds_read_b128 v[198:201], v196 offset:54272
	ds_read_b128 v[202:205], v196 offset:55296
	ds_read_b128 v[206:209], v196 offset:56320
	global_load_lds_dwordx4 v[232:233], off
	v_lshl_add_u64 v[232:233], v[242:243], 0, s[78:79]
	s_mov_b32 m0, s37
	s_nop 0
	global_load_lds_dwordx4 v[232:233], off
	s_barrier
; template <bool PERM, class SchedT, class Epi>
; __device__ __forceinline__ void gemm_phase(LAS unsigned char* lds, const SchedT& S, const Epi& E) {
;     ...
;             G_WAIT_V(6); G_BAR; G_MMA(1, 1, At, B1); G_BAR;
;             G_LDB(B0, 1, 0); G_SCHED; G_LDA(At, 1, 0); G_STA(G_SA(0, 1), a2 + HSTEP(wlda), wlda);
;             G_WAIT_L(8); G_BAR; G_WAIT_L(0); G_MMA(0, 0, At, B0); G_BAR; G_SCHED;
;             G_LDB(B1, 1, 1); G_STB(G_SB(1, 0), b3, wK);
;             G_BAR; G_WAIT_L(0); G_MMA(0, 1, At, B1); G_BAR;
;             G_LDA(At, 1, 1); G_STA(G_SA(1, 0), a3, wlda);
;             G_BAR; G_WAIT_L(0); G_MMA(1, 0, At, B0); G_BAR; G_SCHED;
;             G_STB(G_SB(1, 1), b3 + HSTEP(wK), wK);
;             G_WAIT_V(6); G_BAR; G_MMA(1, 1, At, B1); G_BAR;
;         }
;     __device__ __forceinline__ void operator()(const f32x4 (&acc)[2][2][4][2], const UnitD& u, int wr, int wc, int fr, int fq) const {
;         const int row0 = u.pm * BM + wr * 64 + fr, col0 = u.pn * BM + wc * 32 + 8 * fq;
;         if (u.kind < 2) {
;             GAS bf16_t* C = (GAS bf16_t*)(unsigned long long)u.C;
; #pragma unroll
;             for (int ai = 0; ai < 2; ++ai)
; #pragma unroll
;                 for (int m = 0; m < 4; ++m) { GAS bf16_t* rowp = C + (size_t)(row0 + ai * HALF + m * 16) * 2048 + col0;
; #pragma unroll
;                     for (int bj = 0; bj < 2; ++bj) { const f32x4 v0 = acc[ai][bj][m][0], v1 = acc[ai][bj][m][1];
;                         u32x4 w; w.x = cvt_pk(v0[0], v0[1]); w.y = cvt_pk(v0[2], v0[3]); w.z = cvt_pk(v1[0], v1[1]); w.w = cvt_pk(v1[2], v1[3]);
;                         *(GAS u32x4*)(rowp + bj * HALF) = w; } }
;         } else {
; #pragma unroll
;             for (int ai = 0; ai < 2; ++ai)
; #pragma unroll
;                 for (int m = 0; m < 4; ++m) { const int row = row0 + ai * HALF + m * 16;
;                     const unsigned char* gp = (const unsigned char*)(proj + (size_t)row * NP + C_G) + col0; const size_t po = (size_t)row * 2048 + col0;
;                     u32x2 g0[2], g1[2], g2[2]; u32x4 a[2], b[2];
; #pragma unroll
;                     for (int bj = 0; bj < 2; ++bj) { g0[bj] = *(const u32x2*)(gp + bj * HALF); g1[bj] = *(const u32x2*)(gp + 2048 + bj * HALF); g2[bj] = *(const u32x2*)(gp + 4096 + bj * HALF);
;                         a[bj] = *(const u32x4*)(PA + po + bj * HALF); b[bj] = *(const u32x4*)(PB + po + bj * HALF); }
	s_waitcnt lgkmcnt(0)
	s_setprio 1
	s_waitcnt lgkmcnt(0)
	v_mfma_f32_16x16x32_bf16 v[62:65], v[134:137], v[160:163], v[62:65]
	v_mfma_f32_16x16x32_bf16 v[58:61], v[148:151], v[160:163], v[58:61]
	v_mfma_f32_16x16x32_bf16 v[54:57], v[134:137], v[168:171], v[54:57]
	v_mfma_f32_16x16x32_bf16 v[50:53], v[148:151], v[168:171], v[50:53]
	v_mfma_f32_16x16x32_bf16 v[38:41], v[134:137], v[176:179], v[38:41]
	v_mfma_f32_16x16x32_bf16 v[34:37], v[148:151], v[176:179], v[34:37]
	v_mfma_f32_16x16x32_bf16 v[22:25], v[134:137], v[202:205], v[22:25]
	v_mfma_f32_16x16x32_bf16 v[18:21], v[148:151], v[202:205], v[18:21]
	v_mfma_f32_16x16x32_bf16 v[62:65], v[144:147], v[164:167], v[62:65]
	v_mfma_f32_16x16x32_bf16 v[58:61], v[152:155], v[164:167], v[58:61]
	v_mfma_f32_16x16x32_bf16 v[54:57], v[144:147], v[172:175], v[54:57]
	v_mfma_f32_16x16x32_bf16 v[50:53], v[152:155], v[172:175], v[50:53]
	v_mfma_f32_16x16x32_bf16 v[38:41], v[144:147], v[198:201], v[38:41]
	v_mfma_f32_16x16x32_bf16 v[34:37], v[152:155], v[198:201], v[34:37]
	v_mfma_f32_16x16x32_bf16 v[22:25], v[144:147], v[206:209], v[22:25]
	v_mfma_f32_16x16x32_bf16 v[18:21], v[152:155], v[206:209], v[18:21]
	s_setprio 0
	s_barrier
	s_add_i32 s24, s24, s5
	v_lshl_add_u64 v[134:135], v[156:157], 0, s[78:79]
	s_mov_b32 m0, s24
	s_nop 0
	global_load_lds_dwordx4 v[134:135], off
	v_lshl_add_u64 v[134:135], v[230:231], 0, s[78:79]
	s_add_i32 m0, s24, 0x2000
	s_nop 0
	global_load_lds_dwordx4 v[134:135], off
	s_waitcnt vmcnt(6)
	s_barrier
	s_setprio 1
	v_mfma_f32_16x16x32_bf16 v[46:49], v[210:213], v[160:163], v[46:49]
	v_mfma_f32_16x16x32_bf16 v[42:45], v[218:221], v[160:163], v[42:45]
	v_mfma_f32_16x16x32_bf16 v[30:33], v[210:213], v[168:171], v[30:33]
	v_mfma_f32_16x16x32_bf16 v[26:29], v[218:221], v[168:171], v[26:29]
	v_mfma_f32_16x16x32_bf16 v[14:17], v[210:213], v[176:179], v[14:17]
	v_mfma_f32_16x16x32_bf16 v[10:13], v[218:221], v[176:179], v[10:13]
	v_mfma_f32_16x16x32_bf16 v[6:9], v[210:213], v[202:205], v[6:9]
	v_mfma_f32_16x16x32_bf16 v[2:5], v[218:221], v[202:205], v[2:5]
	v_mfma_f32_16x16x32_bf16 v[46:49], v[214:217], v[164:167], v[46:49]
	v_mfma_f32_16x16x32_bf16 v[42:45], v[222:225], v[164:167], v[42:45]
	v_mfma_f32_16x16x32_bf16 v[30:33], v[214:217], v[172:175], v[30:33]
	v_mfma_f32_16x16x32_bf16 v[26:29], v[222:225], v[172:175], v[26:29]
	v_mfma_f32_16x16x32_bf16 v[14:17], v[214:217], v[198:201], v[14:17]
	v_mfma_f32_16x16x32_bf16 v[10:13], v[222:225], v[198:201], v[10:13]
	v_mfma_f32_16x16x32_bf16 v[6:9], v[214:217], v[206:209], v[6:9]
	v_mfma_f32_16x16x32_bf16 v[2:5], v[222:225], v[206:209], v[2:5]
	s_setprio 0
	s_add_u32 s22, s22, 0x100
	s_addc_u32 s23, s23, 0
	s_add_u32 s21, s21, 0x100
	s_addc_u32 s46, s46, 0
	s_cmp_ge_u32 s47, s9
	s_barrier
	s_cbranch_scc0 .LBB0_44
	v_lshl_add_u32 v144, s43, 8, v193
	v_lshl_or_b32 v150, s42, 8, v195
	s_lshl_b32 vcc_lo, s43, 3
	s_add_u32 vcc_lo, vcc_lo, s42
	s_lshl_b32 vcc_lo, vcc_lo, 17
	v_lshl_add_u32 v145, v193, 8, v195
	v_lshlrev_b32_e32 v145, 1, v145
	v_add_u32_e32 v145, vcc_lo, v145
	s_cmp_lt_i32 s41, 2
	s_cbranch_scc1 .Lg3_k01
	v_readlane_b32 s20, v249, 2
	v_readlane_b32 s21, v249, 3
	v_lshl_add_u32 v151, v144, 11, v150
	v_lshlrev_b32_e32 v151, 1, v151
	v_mul_lo_u32 v146, v144, s3
	v_add_u32_e32 v146, v146, v150
	v_add_u32_e32 v146, 0x5880, v146
	v_mov_b32_e32 v147, v145
	v_mov_b32_e32 v148, v146
	global_load_dwordx2 v[130:131], v148, s[20:21] offset:-2048
	global_load_dwordx2 v[132:133], v148, s[20:21]
	global_load_dwordx2 v[134:135], v148, s[20:21] offset:2048
	global_load_dwordx2 v[136:137], v148, s[20:21] offset:-1920
	global_load_dwordx2 v[160:161], v148, s[20:21] offset:128
	global_load_dwordx2 v[162:163], v148, s[20:21] offset:2176
	global_load_dwordx4 v[164:167], v147, s[58:59]
	global_load_dwordx4 v[168:171], v147, s[60:61]
	global_load_dwordx4 v[172:175], v147, s[58:59] offset:256
	global_load_dwordx4 v[176:179], v147, s[60:61] offset:256
	v_add_u32_e32 v147, 0x2000, v145
	v_add_u32_e32 v148, 0x82000, v146
	global_load_dwordx2 v[198:199], v148, s[20:21] offset:-2048
	global_load_dwordx2 v[200:201], v148, s[20:21]
	global_load_dwordx2 v[202:203], v148, s[20:21] offset:2048
	global_load_dwordx2 v[204:205], v148, s[20:21] offset:-1920
	global_load_dwordx2 v[206:207], v148, s[20:21] offset:128
	global_load_dwordx2 v[208:209], v148, s[20:21] offset:2176
	global_load_dwordx4 v[210:213], v147, s[58:59]
	global_load_dwordx4 v[214:217], v147, s[60:61]
	global_load_dwordx4 v[218:221], v147, s[58:59] offset:256
	global_load_dwordx4 v[222:225], v147, s[60:61] offset:256
	ds_write_b128 v251, v[126:129]
	ds_read_b128 v[126:129], v252
	ds_write_b128 v251, v[122:125]
	ds_read_b128 v[122:125], v252
	ds_write_b128 v251, v[110:113]
	ds_read_b128 v[110:113], v252
	ds_write_b128 v251, v[106:109]
	ds_read_b128 v[106:109], v252
	v_mov_b32_e32 v149, v151
	s_waitcnt vmcnt(10)
	s_waitcnt lgkmcnt(4)
; __device__ __forceinline__ void unpack8(const u32x4 w, float* f) { f[0] = bflo(w.x); f[1] = bfhi(w.x); f[2] = bflo(w.y); f[3] = bfhi(w.y); f[4] = bflo(w.z); f[5] = bfhi(w.z); f[6] = bflo(w.w); f[7] = bfhi(w.w); }
; __device__ __forceinline__ u32x4 pack8(const float* f) { u32x4 w; w.x = cvt_pk(f[0], f[1]); w.y = cvt_pk(f[2], f[3]); w.z = cvt_pk(f[4], f[5]); w.w = cvt_pk(f[6], f[7]); return w; }
;     __device__ __forceinline__ void operator()(const f32x4 (&acc)[2][2][4][2], const UnitD& u, int wr, int wc, int fr, int fq) const {
;     ...
;             for (int ai = 0; ai < 2; ++ai)
; #pragma unroll
;                 for (int m = 0; m < 4; ++m) { const int row = row0 + ai * HALF + m * 16;
;                     const unsigned char* gp = (const unsigned char*)(proj + (size_t)row * NP + C_G) + col0; const size_t po = (size_t)row * 2048 + col0;
;                     u32x2 g0[2], g1[2], g2[2]; u32x4 a[2], b[2];
; #pragma unroll
;                     for (int bj = 0; bj < 2; ++bj) { g0[bj] = *(const u32x2*)(gp + bj * HALF); g1[bj] = *(const u32x2*)(gp + 2048 + bj * HALF); g2[bj] = *(const u32x2*)(gp + 4096 + bj * HALF);
;                         a[bj] = *(const u32x4*)(PA + po + bj * HALF); b[bj] = *(const u32x4*)(PB + po + bj * HALF); }
; #pragma unroll
;                     for (int bj = 0; bj < 2; ++bj) { float f0[8], f1[8], f2[8], fa[8], fb[8], o[8];
;                         unpack_u8(g0[bj], f0); unpack_u8(g1[bj], f1); unpack_u8(g2[bj], f2); unpack8(a[bj], fa); unpack8(b[bj], fb);
;                         const f32x4 v0 = acc[ai][bj][m][0], v1 = acc[ai][bj][m][1];
; #pragma unroll
;                         for (int j = 0; j < 4; ++j) { o[j] = f0[j] * fa[j] + f1[j] * fb[j] + f2[j] * v0[j]; o[4 + j] = f0[4 + j] * fa[4 + j] + f1[4 + j] * fb[4 + j] + f2[4 + j] * v1[j]; }
;                         *(u32x4*)(H + po + bj * HALF) = pack8(o); } }
	v_cvt_f32_ubyte0_e32 v152, v130
	v_cvt_f32_ubyte0_e32 v153, v132
	v_cvt_f32_ubyte0_e32 v154, v134
	v_lshlrev_b32_e32 v155, 16, v164
	v_lshlrev_b32_e32 v156, 16, v168
	v_mul_f32_e32 v152, 0x3b808081, v152
	v_mul_f32_e32 v153, 0x3b808081, v153
	v_mul_f32_e32 v154, 0x3b808081, v154
	v_mul_f32_e32 v157, v152, v155
	v_fmac_f32_e32 v157, v153, v156
	v_fma_f32 v126, v154, v126, v157
	v_cvt_f32_ubyte1_e32 v152, v130
	v_cvt_f32_ubyte1_e32 v153, v132
	v_cvt_f32_ubyte1_e32 v154, v134
	v_and_b32_e32 v155, 0xffff0000, v164
	v_and_b32_e32 v156, 0xffff0000, v168
	v_mul_f32_e32 v152, 0x3b808081, v152
	v_mul_f32_e32 v153, 0x3b808081, v153
	v_mul_f32_e32 v154, 0x3b808081, v154
	v_mul_f32_e32 v157, v152, v155
	v_fmac_f32_e32 v157, v153, v156
	v_fma_f32 v127, v154, v127, v157
	v_cvt_f32_ubyte2_e32 v152, v130
	v_cvt_f32_ubyte2_e32 v153, v132
	v_cvt_f32_ubyte2_e32 v154, v134
	v_lshlrev_b32_e32 v155, 16, v165
	v_lshlrev_b32_e32 v156, 16, v169
	v_mul_f32_e32 v152, 0x3b808081, v152
	v_mul_f32_e32 v153, 0x3b808081, v153
	v_mul_f32_e32 v154, 0x3b808081, v154
	v_mul_f32_e32 v157, v152, v155
	v_fmac_f32_e32 v157, v153, v156
	v_fma_f32 v128, v154, v128, v157
	v_cvt_f32_ubyte3_e32 v152, v130
	v_cvt_f32_ubyte3_e32 v153, v132
	v_cvt_f32_ubyte3_e32 v154, v134
	v_and_b32_e32 v155, 0xffff0000, v165
	v_and_b32_e32 v156, 0xffff0000, v169
	v_mul_f32_e32 v152, 0x3b808081, v152
	v_mul_f32_e32 v153, 0x3b808081, v153
	v_mul_f32_e32 v154, 0x3b808081, v154
	v_mul_f32_e32 v157, v152, v155
	v_fmac_f32_e32 v157, v153, v156
	v_fma_f32 v129, v154, v129, v157
	v_cvt_f32_ubyte0_e32 v152, v131
	v_cvt_f32_ubyte0_e32 v153, v133
	v_cvt_f32_ubyte0_e32 v154, v135
	v_lshlrev_b32_e32 v155, 16, v166
	v_lshlrev_b32_e32 v156, 16, v170
	v_mul_f32_e32 v152, 0x3b808081, v152
	v_mul_f32_e32 v153, 0x3b808081, v153
	v_mul_f32_e32 v154, 0x3b808081, v154
	v_mul_f32_e32 v157, v152, v155
	v_fmac_f32_e32 v157, v153, v156
	v_fma_f32 v122, v154, v122, v157
	v_cvt_f32_ubyte1_e32 v152, v131
	v_cvt_f32_ubyte1_e32 v153, v133
	v_cvt_f32_ubyte1_e32 v154, v135
	v_and_b32_e32 v155, 0xffff0000, v166
	v_and_b32_e32 v156, 0xffff0000, v170
	v_mul_f32_e32 v152, 0x3b808081, v152
	v_mul_f32_e32 v153, 0x3b808081, v153
	v_mul_f32_e32 v154, 0x3b808081, v154
	v_mul_f32_e32 v157, v152, v155
	v_fmac_f32_e32 v157, v153, v156
	v_fma_f32 v123, v154, v123, v157
	v_cvt_f32_ubyte2_e32 v152, v131
	v_cvt_f32_ubyte2_e32 v153, v133
	v_cvt_f32_ubyte2_e32 v154, v135
	v_lshlrev_b32_e32 v155, 16, v167
	v_lshlrev_b32_e32 v156, 16, v171
	v_mul_f32_e32 v152, 0x3b808081, v152
	v_mul_f32_e32 v153, 0x3b808081, v153
	v_mul_f32_e32 v154, 0x3b808081, v154
	v_mul_f32_e32 v157, v152, v155
	v_fmac_f32_e32 v157, v153, v156
	v_fma_f32 v124, v154, v124, v157
	v_cvt_f32_ubyte3_e32 v152, v131
	v_cvt_f32_ubyte3_e32 v153, v133
	v_cvt_f32_ubyte3_e32 v154, v135
	v_and_b32_e32 v155, 0xffff0000, v167
	v_and_b32_e32 v156, 0xffff0000, v171
	v_mul_f32_e32 v152, 0x3b808081, v152
	v_mul_f32_e32 v153, 0x3b808081, v153
	v_mul_f32_e32 v154, 0x3b808081, v154
	v_mul_f32_e32 v157, v152, v155
	v_fmac_f32_e32 v157, v153, v156
	v_fma_f32 v125, v154, v125, v157
	v_cvt_pk_bf16_f32 v126, v126, v127
	v_cvt_pk_bf16_f32 v127, v128, v129
	v_cvt_pk_bf16_f32 v128, v122, v123
	v_cvt_pk_bf16_f32 v129, v124, v125
	global_store_dwordx4 v149, v[126:129], s[62:63]
	s_waitcnt lgkmcnt(0)
	v_cvt_f32_ubyte0_e32 v152, v136
	v_cvt_f32_ubyte0_e32 v153, v160
	v_cvt_f32_ubyte0_e32 v154, v162
	v_lshlrev_b32_e32 v155, 16, v172
	v_lshlrev_b32_e32 v156, 16, v176
	v_mul_f32_e32 v152, 0x3b808081, v152
	v_mul_f32_e32 v153, 0x3b808081, v153
	v_mul_f32_e32 v154, 0x3b808081, v154
	v_mul_f32_e32 v157, v152, v155
	v_fmac_f32_e32 v157, v153, v156
	v_fma_f32 v110, v154, v110, v157
	v_cvt_f32_ubyte1_e32 v152, v136
	v_cvt_f32_ubyte1_e32 v153, v160
	v_cvt_f32_ubyte1_e32 v154, v162
	v_and_b32_e32 v155, 0xffff0000, v172
	v_and_b32_e32 v156, 0xffff0000, v176
	v_mul_f32_e32 v152, 0x3b808081, v152
	v_mul_f32_e32 v153, 0x3b808081, v153
	v_mul_f32_e32 v154, 0x3b808081, v154
	v_mul_f32_e32 v157, v152, v155
	v_fmac_f32_e32 v157, v153, v156
	v_fma_f32 v111, v154, v111, v157
	v_cvt_f32_ubyte2_e32 v152, v136
	v_cvt_f32_ubyte2_e32 v153, v160
	v_cvt_f32_ubyte2_e32 v154, v162
	v_lshlrev_b32_e32 v155, 16, v173
	v_lshlrev_b32_e32 v156, 16, v177
	v_mul_f32_e32 v152, 0x3b808081, v152
	v_mul_f32_e32 v153, 0x3b808081, v153
	v_mul_f32_e32 v154, 0x3b808081, v154
	v_mul_f32_e32 v157, v152, v155
	v_fmac_f32_e32 v157, v153, v156
	v_fma_f32 v112, v154, v112, v157
	v_cvt_f32_ubyte3_e32 v152, v136
	v_cvt_f32_ubyte3_e32 v153, v160
	v_cvt_f32_ubyte3_e32 v154, v162
	v_and_b32_e32 v155, 0xffff0000, v173
	v_and_b32_e32 v156, 0xffff0000, v177
	v_mul_f32_e32 v152, 0x3b808081, v152
	v_mul_f32_e32 v153, 0x3b808081, v153
	v_mul_f32_e32 v154, 0x3b808081, v154
	v_mul_f32_e32 v157, v152, v155
	v_fmac_f32_e32 v157, v153, v156
	v_fma_f32 v113, v154, v113, v157
	v_cvt_f32_ubyte0_e32 v152, v137
	v_cvt_f32_ubyte0_e32 v153, v161
	v_cvt_f32_ubyte0_e32 v154, v163
	v_lshlrev_b32_e32 v155, 16, v174
	v_lshlrev_b32_e32 v156, 16, v178
	v_mul_f32_e32 v152, 0x3b808081, v152
	v_mul_f32_e32 v153, 0x3b808081, v153
	v_mul_f32_e32 v154, 0x3b808081, v154
	v_mul_f32_e32 v157, v152, v155
	v_fmac_f32_e32 v157, v153, v156
	v_fma_f32 v106, v154, v106, v157
	v_cvt_f32_ubyte1_e32 v152, v137
	v_cvt_f32_ubyte1_e32 v153, v161
	v_cvt_f32_ubyte1_e32 v154, v163
	v_and_b32_e32 v155, 0xffff0000, v174
	v_and_b32_e32 v156, 0xffff0000, v178
	v_mul_f32_e32 v152, 0x3b808081, v152
	v_mul_f32_e32 v153, 0x3b808081, v153
	v_mul_f32_e32 v154, 0x3b808081, v154
	v_mul_f32_e32 v157, v152, v155
	v_fmac_f32_e32 v157, v153, v156
	v_fma_f32 v107, v154, v107, v157
	v_cvt_f32_ubyte2_e32 v152, v137
; __device__ __forceinline__ void unpack8(const u32x4 w, float* f) { f[0] = bflo(w.x); f[1] = bfhi(w.x); f[2] = bflo(w.y); f[3] = bfhi(w.y); f[4] = bflo(w.z); f[5] = bfhi(w.z); f[6] = bflo(w.w); f[7] = bfhi(w.w); }
; __device__ __forceinline__ u32x4 pack8(const float* f) { u32x4 w; w.x = cvt_pk(f[0], f[1]); w.y = cvt_pk(f[2], f[3]); w.z = cvt_pk(f[4], f[5]); w.w = cvt_pk(f[6], f[7]); return w; }
;     __device__ __forceinline__ void operator()(const f32x4 (&acc)[2][2][4][2], const UnitD& u, int wr, int wc, int fr, int fq) const {
;     ...
;             for (int ai = 0; ai < 2; ++ai)
; #pragma unroll
;                 for (int m = 0; m < 4; ++m) { const int row = row0 + ai * HALF + m * 16;
;                     const unsigned char* gp = (const unsigned char*)(proj + (size_t)row * NP + C_G) + col0; const size_t po = (size_t)row * 2048 + col0;
;                     u32x2 g0[2], g1[2], g2[2]; u32x4 a[2], b[2];
; #pragma unroll
;                     for (int bj = 0; bj < 2; ++bj) { g0[bj] = *(const u32x2*)(gp + bj * HALF); g1[bj] = *(const u32x2*)(gp + 2048 + bj * HALF); g2[bj] = *(const u32x2*)(gp + 4096 + bj * HALF);
;                         a[bj] = *(const u32x4*)(PA + po + bj * HALF); b[bj] = *(const u32x4*)(PB + po + bj * HALF); }
; #pragma unroll
;                     for (int bj = 0; bj < 2; ++bj) { float f0[8], f1[8], f2[8], fa[8], fb[8], o[8];
;                         unpack_u8(g0[bj], f0); unpack_u8(g1[bj], f1); unpack_u8(g2[bj], f2); unpack8(a[bj], fa); unpack8(b[bj], fb);
;                         const f32x4 v0 = acc[ai][bj][m][0], v1 = acc[ai][bj][m][1];
; #pragma unroll
;                         for (int j = 0; j < 4; ++j) { o[j] = f0[j] * fa[j] + f1[j] * fb[j] + f2[j] * v0[j]; o[4 + j] = f0[4 + j] * fa[4 + j] + f1[4 + j] * fb[4 + j] + f2[4 + j] * v1[j]; }
;                         *(u32x4*)(H + po + bj * HALF) = pack8(o); } }
	v_cvt_f32_ubyte2_e32 v153, v161
	v_cvt_f32_ubyte2_e32 v154, v163
	v_lshlrev_b32_e32 v155, 16, v175
	v_lshlrev_b32_e32 v156, 16, v179
	v_mul_f32_e32 v152, 0x3b808081, v152
	v_mul_f32_e32 v153, 0x3b808081, v153
	v_mul_f32_e32 v154, 0x3b808081, v154
	v_mul_f32_e32 v157, v152, v155
	v_fmac_f32_e32 v157, v153, v156
	v_fma_f32 v108, v154, v108, v157
	v_cvt_f32_ubyte3_e32 v152, v137
	v_cvt_f32_ubyte3_e32 v153, v161
	v_cvt_f32_ubyte3_e32 v154, v163
	v_and_b32_e32 v155, 0xffff0000, v175
	v_and_b32_e32 v156, 0xffff0000, v179
	v_mul_f32_e32 v152, 0x3b808081, v152
	v_mul_f32_e32 v153, 0x3b808081, v153
	v_mul_f32_e32 v154, 0x3b808081, v154
	v_mul_f32_e32 v157, v152, v155
	v_fmac_f32_e32 v157, v153, v156
	v_fma_f32 v109, v154, v109, v157
	v_cvt_pk_bf16_f32 v110, v110, v111
	v_cvt_pk_bf16_f32 v111, v112, v113
	v_cvt_pk_bf16_f32 v112, v106, v107
	v_cvt_pk_bf16_f32 v113, v108, v109
	global_store_dwordx4 v149, v[110:113], s[62:63] offset:256
	v_add_u32_e32 v147, 0x4000, v145
	v_add_u32_e32 v148, 0x104000, v146
	global_load_dwordx2 v[130:131], v148, s[20:21] offset:-2048
	global_load_dwordx2 v[132:133], v148, s[20:21]
	global_load_dwordx2 v[134:135], v148, s[20:21] offset:2048
	global_load_dwordx2 v[136:137], v148, s[20:21] offset:-1920
	global_load_dwordx2 v[160:161], v148, s[20:21] offset:128
	global_load_dwordx2 v[162:163], v148, s[20:21] offset:2176
	global_load_dwordx4 v[164:167], v147, s[58:59]
	global_load_dwordx4 v[168:171], v147, s[60:61]
	global_load_dwordx4 v[172:175], v147, s[58:59] offset:256
	global_load_dwordx4 v[176:179], v147, s[60:61] offset:256
	ds_write_b128 v251, v[118:121]
	ds_read_b128 v[118:121], v252
	ds_write_b128 v251, v[114:117]
	ds_read_b128 v[114:117], v252
	ds_write_b128 v251, v[94:97]
	ds_read_b128 v[94:97], v252
	ds_write_b128 v251, v[90:93]
	ds_read_b128 v[90:93], v252
	v_add_u32_e32 v149, 0x10000, v151
	s_waitcnt vmcnt(12)
	s_waitcnt lgkmcnt(4)
	v_cvt_f32_ubyte0_e32 v152, v198
	v_cvt_f32_ubyte0_e32 v153, v200
	v_cvt_f32_ubyte0_e32 v154, v202
	v_lshlrev_b32_e32 v155, 16, v210
	v_lshlrev_b32_e32 v156, 16, v214
	v_mul_f32_e32 v152, 0x3b808081, v152
	v_mul_f32_e32 v153, 0x3b808081, v153
	v_mul_f32_e32 v154, 0x3b808081, v154
	v_mul_f32_e32 v157, v152, v155
	v_fmac_f32_e32 v157, v153, v156
	v_fma_f32 v118, v154, v118, v157
	v_cvt_f32_ubyte1_e32 v152, v198
	v_cvt_f32_ubyte1_e32 v153, v200
	v_cvt_f32_ubyte1_e32 v154, v202
	v_and_b32_e32 v155, 0xffff0000, v210
	v_and_b32_e32 v156, 0xffff0000, v214
	v_mul_f32_e32 v152, 0x3b808081, v152
	v_mul_f32_e32 v153, 0x3b808081, v153
	v_mul_f32_e32 v154, 0x3b808081, v154
	v_mul_f32_e32 v157, v152, v155
	v_fmac_f32_e32 v157, v153, v156
	v_fma_f32 v119, v154, v119, v157
	v_cvt_f32_ubyte2_e32 v152, v198
	v_cvt_f32_ubyte2_e32 v153, v200
	v_cvt_f32_ubyte2_e32 v154, v202
	v_lshlrev_b32_e32 v155, 16, v211
	v_lshlrev_b32_e32 v156, 16, v215
	v_mul_f32_e32 v152, 0x3b808081, v152
	v_mul_f32_e32 v153, 0x3b808081, v153
	v_mul_f32_e32 v154, 0x3b808081, v154
	v_mul_f32_e32 v157, v152, v155
	v_fmac_f32_e32 v157, v153, v156
	v_fma_f32 v120, v154, v120, v157
	v_cvt_f32_ubyte3_e32 v152, v198
	v_cvt_f32_ubyte3_e32 v153, v200
	v_cvt_f32_ubyte3_e32 v154, v202
	v_and_b32_e32 v155, 0xffff0000, v211
	v_and_b32_e32 v156, 0xffff0000, v215
	v_mul_f32_e32 v152, 0x3b808081, v152
	v_mul_f32_e32 v153, 0x3b808081, v153
	v_mul_f32_e32 v154, 0x3b808081, v154
	v_mul_f32_e32 v157, v152, v155
	v_fmac_f32_e32 v157, v153, v156
	v_fma_f32 v121, v154, v121, v157
	v_cvt_f32_ubyte0_e32 v152, v199
	v_cvt_f32_ubyte0_e32 v153, v201
	v_cvt_f32_ubyte0_e32 v154, v203
	v_lshlrev_b32_e32 v155, 16, v212
	v_lshlrev_b32_e32 v156, 16, v216
	v_mul_f32_e32 v152, 0x3b808081, v152
	v_mul_f32_e32 v153, 0x3b808081, v153
	v_mul_f32_e32 v154, 0x3b808081, v154
	v_mul_f32_e32 v157, v152, v155
	v_fmac_f32_e32 v157, v153, v156
	v_fma_f32 v114, v154, v114, v157
	v_cvt_f32_ubyte1_e32 v152, v199
	v_cvt_f32_ubyte1_e32 v153, v201
	v_cvt_f32_ubyte1_e32 v154, v203
	v_and_b32_e32 v155, 0xffff0000, v212
	v_and_b32_e32 v156, 0xffff0000, v216
	v_mul_f32_e32 v152, 0x3b808081, v152
	v_mul_f32_e32 v153, 0x3b808081, v153
	v_mul_f32_e32 v154, 0x3b808081, v154
	v_mul_f32_e32 v157, v152, v155
	v_fmac_f32_e32 v157, v153, v156
	v_fma_f32 v115, v154, v115, v157
	v_cvt_f32_ubyte2_e32 v152, v199
	v_cvt_f32_ubyte2_e32 v153, v201
	v_cvt_f32_ubyte2_e32 v154, v203
	v_lshlrev_b32_e32 v155, 16, v213
	v_lshlrev_b32_e32 v156, 16, v217
	v_mul_f32_e32 v152, 0x3b808081, v152
	v_mul_f32_e32 v153, 0x3b808081, v153
	v_mul_f32_e32 v154, 0x3b808081, v154
	v_mul_f32_e32 v157, v152, v155
	v_fmac_f32_e32 v157, v153, v156
	v_fma_f32 v116, v154, v116, v157
	v_cvt_f32_ubyte3_e32 v152, v199
	v_cvt_f32_ubyte3_e32 v153, v201
	v_cvt_f32_ubyte3_e32 v154, v203
	v_and_b32_e32 v155, 0xffff0000, v213
	v_and_b32_e32 v156, 0xffff0000, v217
	v_mul_f32_e32 v152, 0x3b808081, v152
	v_mul_f32_e32 v153, 0x3b808081, v153
	v_mul_f32_e32 v154, 0x3b808081, v154
	v_mul_f32_e32 v157, v152, v155
	v_fmac_f32_e32 v157, v153, v156
	v_fma_f32 v117, v154, v117, v157
	v_cvt_pk_bf16_f32 v118, v118, v119
	v_cvt_pk_bf16_f32 v119, v120, v121
	v_cvt_pk_bf16_f32 v120, v114, v115
	v_cvt_pk_bf16_f32 v121, v116, v117
	global_store_dwordx4 v149, v[118:121], s[62:63]
	s_waitcnt lgkmcnt(0)
; __device__ __forceinline__ void unpack8(const u32x4 w, float* f) { f[0] = bflo(w.x); f[1] = bfhi(w.x); f[2] = bflo(w.y); f[3] = bfhi(w.y); f[4] = bflo(w.z); f[5] = bfhi(w.z); f[6] = bflo(w.w); f[7] = bfhi(w.w); }
; __device__ __forceinline__ u32x4 pack8(const float* f) { u32x4 w; w.x = cvt_pk(f[0], f[1]); w.y = cvt_pk(f[2], f[3]); w.z = cvt_pk(f[4], f[5]); w.w = cvt_pk(f[6], f[7]); return w; }
;     __device__ __forceinline__ void operator()(const f32x4 (&acc)[2][2][4][2], const UnitD& u, int wr, int wc, int fr, int fq) const {
;     ...
;             for (int ai = 0; ai < 2; ++ai)
; #pragma unroll
;                 for (int m = 0; m < 4; ++m) { const int row = row0 + ai * HALF + m * 16;
;                     const unsigned char* gp = (const unsigned char*)(proj + (size_t)row * NP + C_G) + col0; const size_t po = (size_t)row * 2048 + col0;
;                     u32x2 g0[2], g1[2], g2[2]; u32x4 a[2], b[2];
; #pragma unroll
;                     for (int bj = 0; bj < 2; ++bj) { g0[bj] = *(const u32x2*)(gp + bj * HALF); g1[bj] = *(const u32x2*)(gp + 2048 + bj * HALF); g2[bj] = *(const u32x2*)(gp + 4096 + bj * HALF);
;                         a[bj] = *(const u32x4*)(PA + po + bj * HALF); b[bj] = *(const u32x4*)(PB + po + bj * HALF); }
; #pragma unroll
;                     for (int bj = 0; bj < 2; ++bj) { float f0[8], f1[8], f2[8], fa[8], fb[8], o[8];
;                         unpack_u8(g0[bj], f0); unpack_u8(g1[bj], f1); unpack_u8(g2[bj], f2); unpack8(a[bj], fa); unpack8(b[bj], fb);
;                         const f32x4 v0 = acc[ai][bj][m][0], v1 = acc[ai][bj][m][1];
; #pragma unroll
;                         for (int j = 0; j < 4; ++j) { o[j] = f0[j] * fa[j] + f1[j] * fb[j] + f2[j] * v0[j]; o[4 + j] = f0[4 + j] * fa[4 + j] + f1[4 + j] * fb[4 + j] + f2[4 + j] * v1[j]; }
;                         *(u32x4*)(H + po + bj * HALF) = pack8(o); } }
	v_cvt_f32_ubyte0_e32 v152, v204
	v_cvt_f32_ubyte0_e32 v153, v206
	v_cvt_f32_ubyte0_e32 v154, v208
	v_lshlrev_b32_e32 v155, 16, v218
	v_lshlrev_b32_e32 v156, 16, v222
	v_mul_f32_e32 v152, 0x3b808081, v152
	v_mul_f32_e32 v153, 0x3b808081, v153
	v_mul_f32_e32 v154, 0x3b808081, v154
	v_mul_f32_e32 v157, v152, v155
	v_fmac_f32_e32 v157, v153, v156
	v_fma_f32 v94, v154, v94, v157
	v_cvt_f32_ubyte1_e32 v152, v204
	v_cvt_f32_ubyte1_e32 v153, v206
	v_cvt_f32_ubyte1_e32 v154, v208
	v_and_b32_e32 v155, 0xffff0000, v218
	v_and_b32_e32 v156, 0xffff0000, v222
	v_mul_f32_e32 v152, 0x3b808081, v152
	v_mul_f32_e32 v153, 0x3b808081, v153
	v_mul_f32_e32 v154, 0x3b808081, v154
	v_mul_f32_e32 v157, v152, v155
	v_fmac_f32_e32 v157, v153, v156
	v_fma_f32 v95, v154, v95, v157
	v_cvt_f32_ubyte2_e32 v152, v204
	v_cvt_f32_ubyte2_e32 v153, v206
	v_cvt_f32_ubyte2_e32 v154, v208
	v_lshlrev_b32_e32 v155, 16, v219
	v_lshlrev_b32_e32 v156, 16, v223
	v_mul_f32_e32 v152, 0x3b808081, v152
	v_mul_f32_e32 v153, 0x3b808081, v153
	v_mul_f32_e32 v154, 0x3b808081, v154
	v_mul_f32_e32 v157, v152, v155
	v_fmac_f32_e32 v157, v153, v156
	v_fma_f32 v96, v154, v96, v157
	v_cvt_f32_ubyte3_e32 v152, v204
	v_cvt_f32_ubyte3_e32 v153, v206
	v_cvt_f32_ubyte3_e32 v154, v208
	v_and_b32_e32 v155, 0xffff0000, v219
	v_and_b32_e32 v156, 0xffff0000, v223
	v_mul_f32_e32 v152, 0x3b808081, v152
	v_mul_f32_e32 v153, 0x3b808081, v153
	v_mul_f32_e32 v154, 0x3b808081, v154
	v_mul_f32_e32 v157, v152, v155
	v_fmac_f32_e32 v157, v153, v156
	v_fma_f32 v97, v154, v97, v157
	v_cvt_f32_ubyte0_e32 v152, v205
	v_cvt_f32_ubyte0_e32 v153, v207
	v_cvt_f32_ubyte0_e32 v154, v209
	v_lshlrev_b32_e32 v155, 16, v220
	v_lshlrev_b32_e32 v156, 16, v224
	v_mul_f32_e32 v152, 0x3b808081, v152
	v_mul_f32_e32 v153, 0x3b808081, v153
	v_mul_f32_e32 v154, 0x3b808081, v154
	v_mul_f32_e32 v157, v152, v155
	v_fmac_f32_e32 v157, v153, v156
	v_fma_f32 v90, v154, v90, v157
	v_cvt_f32_ubyte1_e32 v152, v205
	v_cvt_f32_ubyte1_e32 v153, v207
	v_cvt_f32_ubyte1_e32 v154, v209
	v_and_b32_e32 v155, 0xffff0000, v220
	v_and_b32_e32 v156, 0xffff0000, v224
	v_mul_f32_e32 v152, 0x3b808081, v152
	v_mul_f32_e32 v153, 0x3b808081, v153
	v_mul_f32_e32 v154, 0x3b808081, v154
	v_mul_f32_e32 v157, v152, v155
	v_fmac_f32_e32 v157, v153, v156
	v_fma_f32 v91, v154, v91, v157
	v_cvt_f32_ubyte2_e32 v152, v205
	v_cvt_f32_ubyte2_e32 v153, v207
	v_cvt_f32_ubyte2_e32 v154, v209
	v_lshlrev_b32_e32 v155, 16, v221
	v_lshlrev_b32_e32 v156, 16, v225
	v_mul_f32_e32 v152, 0x3b808081, v152
	v_mul_f32_e32 v153, 0x3b808081, v153
	v_mul_f32_e32 v154, 0x3b808081, v154
	v_mul_f32_e32 v157, v152, v155
	v_fmac_f32_e32 v157, v153, v156
	v_fma_f32 v92, v154, v92, v157
	v_cvt_f32_ubyte3_e32 v152, v205
	v_cvt_f32_ubyte3_e32 v153, v207
	v_cvt_f32_ubyte3_e32 v154, v209
	v_and_b32_e32 v155, 0xffff0000, v221
	v_and_b32_e32 v156, 0xffff0000, v225
	v_mul_f32_e32 v152, 0x3b808081, v152
	v_mul_f32_e32 v153, 0x3b808081, v153
	v_mul_f32_e32 v154, 0x3b808081, v154
	v_mul_f32_e32 v157, v152, v155
	v_fmac_f32_e32 v157, v153, v156
	v_fma_f32 v93, v154, v93, v157
	v_cvt_pk_bf16_f32 v94, v94, v95
	v_cvt_pk_bf16_f32 v95, v96, v97
	v_cvt_pk_bf16_f32 v96, v90, v91
	v_cvt_pk_bf16_f32 v97, v92, v93
	global_store_dwordx4 v149, v[94:97], s[62:63] offset:256
	v_add_u32_e32 v147, 0x6000, v145
	v_add_u32_e32 v148, 0x186000, v146
	global_load_dwordx2 v[198:199], v148, s[20:21] offset:-2048
	global_load_dwordx2 v[200:201], v148, s[20:21]
	global_load_dwordx2 v[202:203], v148, s[20:21] offset:2048
	global_load_dwordx2 v[204:205], v148, s[20:21] offset:-1920
	global_load_dwordx2 v[206:207], v148, s[20:21] offset:128
	global_load_dwordx2 v[208:209], v148, s[20:21] offset:2176
	global_load_dwordx4 v[210:213], v147, s[58:59]
	global_load_dwordx4 v[214:217], v147, s[60:61]
	global_load_dwordx4 v[218:221], v147, s[58:59] offset:256
	global_load_dwordx4 v[222:225], v147, s[60:61] offset:256
	ds_write_b128 v251, v[102:105]
	ds_read_b128 v[102:105], v252
	ds_write_b128 v251, v[98:101]
	ds_read_b128 v[98:101], v252
	ds_write_b128 v251, v[78:81]
	ds_read_b128 v[78:81], v252
	ds_write_b128 v251, v[74:77]
	ds_read_b128 v[74:77], v252
	v_add_u32_e32 v149, 0x20000, v151
	s_waitcnt vmcnt(12)
	s_waitcnt lgkmcnt(4)
	v_cvt_f32_ubyte0_e32 v152, v130
	v_cvt_f32_ubyte0_e32 v153, v132
	v_cvt_f32_ubyte0_e32 v154, v134
	v_lshlrev_b32_e32 v155, 16, v164
	v_lshlrev_b32_e32 v156, 16, v168
	v_mul_f32_e32 v152, 0x3b808081, v152
	v_mul_f32_e32 v153, 0x3b808081, v153
	v_mul_f32_e32 v154, 0x3b808081, v154
	v_mul_f32_e32 v157, v152, v155
	v_fmac_f32_e32 v157, v153, v156
	v_fma_f32 v102, v154, v102, v157
	v_cvt_f32_ubyte1_e32 v152, v130
	v_cvt_f32_ubyte1_e32 v153, v132
	v_cvt_f32_ubyte1_e32 v154, v134
	v_and_b32_e32 v155, 0xffff0000, v164
	v_and_b32_e32 v156, 0xffff0000, v168
	v_mul_f32_e32 v152, 0x3b808081, v152
	v_mul_f32_e32 v153, 0x3b808081, v153
	v_mul_f32_e32 v154, 0x3b808081, v154
	v_mul_f32_e32 v157, v152, v155
	v_fmac_f32_e32 v157, v153, v156
	v_fma_f32 v103, v154, v103, v157
	v_cvt_f32_ubyte2_e32 v152, v130
	v_cvt_f32_ubyte2_e32 v153, v132
	v_cvt_f32_ubyte2_e32 v154, v134
	v_lshlrev_b32_e32 v155, 16, v165
	v_lshlrev_b32_e32 v156, 16, v169
	v_mul_f32_e32 v152, 0x3b808081, v152
	v_mul_f32_e32 v153, 0x3b808081, v153
	v_mul_f32_e32 v154, 0x3b808081, v154
	v_mul_f32_e32 v157, v152, v155
	v_fmac_f32_e32 v157, v153, v156
	v_fma_f32 v104, v154, v104, v157
	v_cvt_f32_ubyte3_e32 v152, v130
	v_cvt_f32_ubyte3_e32 v153, v132
	v_cvt_f32_ubyte3_e32 v154, v134
	v_and_b32_e32 v155, 0xffff0000, v165
	v_and_b32_e32 v156, 0xffff0000, v169
	v_mul_f32_e32 v152, 0x3b808081, v152
	v_mul_f32_e32 v153, 0x3b808081, v153
	v_mul_f32_e32 v154, 0x3b808081, v154
; __device__ __forceinline__ void unpack8(const u32x4 w, float* f) { f[0] = bflo(w.x); f[1] = bfhi(w.x); f[2] = bflo(w.y); f[3] = bfhi(w.y); f[4] = bflo(w.z); f[5] = bfhi(w.z); f[6] = bflo(w.w); f[7] = bfhi(w.w); }
; __device__ __forceinline__ u32x4 pack8(const float* f) { u32x4 w; w.x = cvt_pk(f[0], f[1]); w.y = cvt_pk(f[2], f[3]); w.z = cvt_pk(f[4], f[5]); w.w = cvt_pk(f[6], f[7]); return w; }
;     __device__ __forceinline__ void operator()(const f32x4 (&acc)[2][2][4][2], const UnitD& u, int wr, int wc, int fr, int fq) const {
;     ...
;             for (int ai = 0; ai < 2; ++ai)
; #pragma unroll
;                 for (int m = 0; m < 4; ++m) { const int row = row0 + ai * HALF + m * 16;
;                     const unsigned char* gp = (const unsigned char*)(proj + (size_t)row * NP + C_G) + col0; const size_t po = (size_t)row * 2048 + col0;
;                     u32x2 g0[2], g1[2], g2[2]; u32x4 a[2], b[2];
; #pragma unroll
;                     for (int bj = 0; bj < 2; ++bj) { g0[bj] = *(const u32x2*)(gp + bj * HALF); g1[bj] = *(const u32x2*)(gp + 2048 + bj * HALF); g2[bj] = *(const u32x2*)(gp + 4096 + bj * HALF);
;                         a[bj] = *(const u32x4*)(PA + po + bj * HALF); b[bj] = *(const u32x4*)(PB + po + bj * HALF); }
; #pragma unroll
;                     for (int bj = 0; bj < 2; ++bj) { float f0[8], f1[8], f2[8], fa[8], fb[8], o[8];
;                         unpack_u8(g0[bj], f0); unpack_u8(g1[bj], f1); unpack_u8(g2[bj], f2); unpack8(a[bj], fa); unpack8(b[bj], fb);
;                         const f32x4 v0 = acc[ai][bj][m][0], v1 = acc[ai][bj][m][1];
; #pragma unroll
;                         for (int j = 0; j < 4; ++j) { o[j] = f0[j] * fa[j] + f1[j] * fb[j] + f2[j] * v0[j]; o[4 + j] = f0[4 + j] * fa[4 + j] + f1[4 + j] * fb[4 + j] + f2[4 + j] * v1[j]; }
;                         *(u32x4*)(H + po + bj * HALF) = pack8(o); } }
	v_mul_f32_e32 v157, v152, v155
	v_fmac_f32_e32 v157, v153, v156
	v_fma_f32 v105, v154, v105, v157
	v_cvt_f32_ubyte0_e32 v152, v131
	v_cvt_f32_ubyte0_e32 v153, v133
	v_cvt_f32_ubyte0_e32 v154, v135
	v_lshlrev_b32_e32 v155, 16, v166
	v_lshlrev_b32_e32 v156, 16, v170
	v_mul_f32_e32 v152, 0x3b808081, v152
	v_mul_f32_e32 v153, 0x3b808081, v153
	v_mul_f32_e32 v154, 0x3b808081, v154
	v_mul_f32_e32 v157, v152, v155
	v_fmac_f32_e32 v157, v153, v156
	v_fma_f32 v98, v154, v98, v157
	v_cvt_f32_ubyte1_e32 v152, v131
	v_cvt_f32_ubyte1_e32 v153, v133
	v_cvt_f32_ubyte1_e32 v154, v135
	v_and_b32_e32 v155, 0xffff0000, v166
	v_and_b32_e32 v156, 0xffff0000, v170
	v_mul_f32_e32 v152, 0x3b808081, v152
	v_mul_f32_e32 v153, 0x3b808081, v153
	v_mul_f32_e32 v154, 0x3b808081, v154
	v_mul_f32_e32 v157, v152, v155
	v_fmac_f32_e32 v157, v153, v156
	v_fma_f32 v99, v154, v99, v157
	v_cvt_f32_ubyte2_e32 v152, v131
	v_cvt_f32_ubyte2_e32 v153, v133
	v_cvt_f32_ubyte2_e32 v154, v135
	v_lshlrev_b32_e32 v155, 16, v167
	v_lshlrev_b32_e32 v156, 16, v171
	v_mul_f32_e32 v152, 0x3b808081, v152
	v_mul_f32_e32 v153, 0x3b808081, v153
	v_mul_f32_e32 v154, 0x3b808081, v154
	v_mul_f32_e32 v157, v152, v155
	v_fmac_f32_e32 v157, v153, v156
	v_fma_f32 v100, v154, v100, v157
	v_cvt_f32_ubyte3_e32 v152, v131
	v_cvt_f32_ubyte3_e32 v153, v133
	v_cvt_f32_ubyte3_e32 v154, v135
	v_and_b32_e32 v155, 0xffff0000, v167
	v_and_b32_e32 v156, 0xffff0000, v171
	v_mul_f32_e32 v152, 0x3b808081, v152
	v_mul_f32_e32 v153, 0x3b808081, v153
	v_mul_f32_e32 v154, 0x3b808081, v154
	v_mul_f32_e32 v157, v152, v155
	v_fmac_f32_e32 v157, v153, v156
	v_fma_f32 v101, v154, v101, v157
	v_cvt_pk_bf16_f32 v102, v102, v103
	v_cvt_pk_bf16_f32 v103, v104, v105
	v_cvt_pk_bf16_f32 v104, v98, v99
	v_cvt_pk_bf16_f32 v105, v100, v101
	global_store_dwordx4 v149, v[102:105], s[62:63]
	s_waitcnt lgkmcnt(0)
	v_cvt_f32_ubyte0_e32 v152, v136
	v_cvt_f32_ubyte0_e32 v153, v160
	v_cvt_f32_ubyte0_e32 v154, v162
	v_lshlrev_b32_e32 v155, 16, v172
	v_lshlrev_b32_e32 v156, 16, v176
	v_mul_f32_e32 v152, 0x3b808081, v152
	v_mul_f32_e32 v153, 0x3b808081, v153
	v_mul_f32_e32 v154, 0x3b808081, v154
	v_mul_f32_e32 v157, v152, v155
	v_fmac_f32_e32 v157, v153, v156
	v_fma_f32 v78, v154, v78, v157
	v_cvt_f32_ubyte1_e32 v152, v136
	v_cvt_f32_ubyte1_e32 v153, v160
	v_cvt_f32_ubyte1_e32 v154, v162
	v_and_b32_e32 v155, 0xffff0000, v172
	v_and_b32_e32 v156, 0xffff0000, v176
	v_mul_f32_e32 v152, 0x3b808081, v152
	v_mul_f32_e32 v153, 0x3b808081, v153
	v_mul_f32_e32 v154, 0x3b808081, v154
	v_mul_f32_e32 v157, v152, v155
	v_fmac_f32_e32 v157, v153, v156
	v_fma_f32 v79, v154, v79, v157
	v_cvt_f32_ubyte2_e32 v152, v136
	v_cvt_f32_ubyte2_e32 v153, v160
	v_cvt_f32_ubyte2_e32 v154, v162
	v_lshlrev_b32_e32 v155, 16, v173
	v_lshlrev_b32_e32 v156, 16, v177
	v_mul_f32_e32 v152, 0x3b808081, v152
	v_mul_f32_e32 v153, 0x3b808081, v153
	v_mul_f32_e32 v154, 0x3b808081, v154
	v_mul_f32_e32 v157, v152, v155
	v_fmac_f32_e32 v157, v153, v156
	v_fma_f32 v80, v154, v80, v157
	v_cvt_f32_ubyte3_e32 v152, v136
	v_cvt_f32_ubyte3_e32 v153, v160
	v_cvt_f32_ubyte3_e32 v154, v162
	v_and_b32_e32 v155, 0xffff0000, v173
	v_and_b32_e32 v156, 0xffff0000, v177
	v_mul_f32_e32 v152, 0x3b808081, v152
	v_mul_f32_e32 v153, 0x3b808081, v153
	v_mul_f32_e32 v154, 0x3b808081, v154
	v_mul_f32_e32 v157, v152, v155
	v_fmac_f32_e32 v157, v153, v156
	v_fma_f32 v81, v154, v81, v157
	v_cvt_f32_ubyte0_e32 v152, v137
	v_cvt_f32_ubyte0_e32 v153, v161
	v_cvt_f32_ubyte0_e32 v154, v163
	v_lshlrev_b32_e32 v155, 16, v174
	v_lshlrev_b32_e32 v156, 16, v178
	v_mul_f32_e32 v152, 0x3b808081, v152
	v_mul_f32_e32 v153, 0x3b808081, v153
	v_mul_f32_e32 v154, 0x3b808081, v154
	v_mul_f32_e32 v157, v152, v155
	v_fmac_f32_e32 v157, v153, v156
	v_fma_f32 v74, v154, v74, v157
	v_cvt_f32_ubyte1_e32 v152, v137
	v_cvt_f32_ubyte1_e32 v153, v161
	v_cvt_f32_ubyte1_e32 v154, v163
	v_and_b32_e32 v155, 0xffff0000, v174
	v_and_b32_e32 v156, 0xffff0000, v178
	v_mul_f32_e32 v152, 0x3b808081, v152
	v_mul_f32_e32 v153, 0x3b808081, v153
	v_mul_f32_e32 v154, 0x3b808081, v154
	v_mul_f32_e32 v157, v152, v155
	v_fmac_f32_e32 v157, v153, v156
	v_fma_f32 v75, v154, v75, v157
	v_cvt_f32_ubyte2_e32 v152, v137
	v_cvt_f32_ubyte2_e32 v153, v161
	v_cvt_f32_ubyte2_e32 v154, v163
	v_lshlrev_b32_e32 v155, 16, v175
	v_lshlrev_b32_e32 v156, 16, v179
	v_mul_f32_e32 v152, 0x3b808081, v152
	v_mul_f32_e32 v153, 0x3b808081, v153
	v_mul_f32_e32 v154, 0x3b808081, v154
	v_mul_f32_e32 v157, v152, v155
	v_fmac_f32_e32 v157, v153, v156
	v_fma_f32 v76, v154, v76, v157
	v_cvt_f32_ubyte3_e32 v152, v137
	v_cvt_f32_ubyte3_e32 v153, v161
	v_cvt_f32_ubyte3_e32 v154, v163
	v_and_b32_e32 v155, 0xffff0000, v175
	v_and_b32_e32 v156, 0xffff0000, v179
	v_mul_f32_e32 v152, 0x3b808081, v152
	v_mul_f32_e32 v153, 0x3b808081, v153
	v_mul_f32_e32 v154, 0x3b808081, v154
	v_mul_f32_e32 v157, v152, v155
	v_fmac_f32_e32 v157, v153, v156
	v_fma_f32 v77, v154, v77, v157
	v_cvt_pk_bf16_f32 v78, v78, v79
	v_cvt_pk_bf16_f32 v79, v80, v81
	v_cvt_pk_bf16_f32 v80, v74, v75
	v_cvt_pk_bf16_f32 v81, v76, v77
	global_store_dwordx4 v149, v[78:81], s[62:63] offset:256
	v_add_u32_e32 v147, 0x10000, v145
	v_add_u32_e32 v148, 0x410000, v146
	global_load_dwordx2 v[130:131], v148, s[20:21] offset:-2048
	global_load_dwordx2 v[132:133], v148, s[20:21]
	global_load_dwordx2 v[134:135], v148, s[20:21] offset:2048
	global_load_dwordx2 v[136:137], v148, s[20:21] offset:-1920
	global_load_dwordx2 v[160:161], v148, s[20:21] offset:128
	global_load_dwordx2 v[162:163], v148, s[20:21] offset:2176
	global_load_dwordx4 v[164:167], v147, s[58:59]
	global_load_dwordx4 v[168:171], v147, s[60:61]
	global_load_dwordx4 v[172:175], v147, s[58:59] offset:256
	global_load_dwordx4 v[176:179], v147, s[60:61] offset:256
	ds_write_b128 v251, v[86:89]
	ds_read_b128 v[86:89], v252
	ds_write_b128 v251, v[82:85]
	ds_read_b128 v[82:85], v252
	ds_write_b128 v251, v[70:73]
	ds_read_b128 v[70:73], v252
	ds_write_b128 v251, v[66:69]
	ds_read_b128 v[66:69], v252
	v_add_u32_e32 v149, 0x30000, v151
	s_waitcnt vmcnt(12)
; __device__ __forceinline__ void unpack8(const u32x4 w, float* f) { f[0] = bflo(w.x); f[1] = bfhi(w.x); f[2] = bflo(w.y); f[3] = bfhi(w.y); f[4] = bflo(w.z); f[5] = bfhi(w.z); f[6] = bflo(w.w); f[7] = bfhi(w.w); }
; __device__ __forceinline__ u32x4 pack8(const float* f) { u32x4 w; w.x = cvt_pk(f[0], f[1]); w.y = cvt_pk(f[2], f[3]); w.z = cvt_pk(f[4], f[5]); w.w = cvt_pk(f[6], f[7]); return w; }
;     __device__ __forceinline__ void operator()(const f32x4 (&acc)[2][2][4][2], const UnitD& u, int wr, int wc, int fr, int fq) const {
;     ...
;             for (int ai = 0; ai < 2; ++ai)
; #pragma unroll
;                 for (int m = 0; m < 4; ++m) { const int row = row0 + ai * HALF + m * 16;
;                     const unsigned char* gp = (const unsigned char*)(proj + (size_t)row * NP + C_G) + col0; const size_t po = (size_t)row * 2048 + col0;
;                     u32x2 g0[2], g1[2], g2[2]; u32x4 a[2], b[2];
; #pragma unroll
;                     for (int bj = 0; bj < 2; ++bj) { g0[bj] = *(const u32x2*)(gp + bj * HALF); g1[bj] = *(const u32x2*)(gp + 2048 + bj * HALF); g2[bj] = *(const u32x2*)(gp + 4096 + bj * HALF);
;                         a[bj] = *(const u32x4*)(PA + po + bj * HALF); b[bj] = *(const u32x4*)(PB + po + bj * HALF); }
; #pragma unroll
;                     for (int bj = 0; bj < 2; ++bj) { float f0[8], f1[8], f2[8], fa[8], fb[8], o[8];
;                         unpack_u8(g0[bj], f0); unpack_u8(g1[bj], f1); unpack_u8(g2[bj], f2); unpack8(a[bj], fa); unpack8(b[bj], fb);
;                         const f32x4 v0 = acc[ai][bj][m][0], v1 = acc[ai][bj][m][1];
; #pragma unroll
;                         for (int j = 0; j < 4; ++j) { o[j] = f0[j] * fa[j] + f1[j] * fb[j] + f2[j] * v0[j]; o[4 + j] = f0[4 + j] * fa[4 + j] + f1[4 + j] * fb[4 + j] + f2[4 + j] * v1[j]; }
;                         *(u32x4*)(H + po + bj * HALF) = pack8(o); } }
	s_waitcnt lgkmcnt(4)
	v_cvt_f32_ubyte0_e32 v152, v198
	v_cvt_f32_ubyte0_e32 v153, v200
	v_cvt_f32_ubyte0_e32 v154, v202
	v_lshlrev_b32_e32 v155, 16, v210
	v_lshlrev_b32_e32 v156, 16, v214
	v_mul_f32_e32 v152, 0x3b808081, v152
	v_mul_f32_e32 v153, 0x3b808081, v153
	v_mul_f32_e32 v154, 0x3b808081, v154
	v_mul_f32_e32 v157, v152, v155
	v_fmac_f32_e32 v157, v153, v156
	v_fma_f32 v86, v154, v86, v157
	v_cvt_f32_ubyte1_e32 v152, v198
	v_cvt_f32_ubyte1_e32 v153, v200
	v_cvt_f32_ubyte1_e32 v154, v202
	v_and_b32_e32 v155, 0xffff0000, v210
	v_and_b32_e32 v156, 0xffff0000, v214
	v_mul_f32_e32 v152, 0x3b808081, v152
	v_mul_f32_e32 v153, 0x3b808081, v153
	v_mul_f32_e32 v154, 0x3b808081, v154
	v_mul_f32_e32 v157, v152, v155
	v_fmac_f32_e32 v157, v153, v156
	v_fma_f32 v87, v154, v87, v157
	v_cvt_f32_ubyte2_e32 v152, v198
	v_cvt_f32_ubyte2_e32 v153, v200
	v_cvt_f32_ubyte2_e32 v154, v202
	v_lshlrev_b32_e32 v155, 16, v211
	v_lshlrev_b32_e32 v156, 16, v215
	v_mul_f32_e32 v152, 0x3b808081, v152
	v_mul_f32_e32 v153, 0x3b808081, v153
	v_mul_f32_e32 v154, 0x3b808081, v154
	v_mul_f32_e32 v157, v152, v155
	v_fmac_f32_e32 v157, v153, v156
	v_fma_f32 v88, v154, v88, v157
	v_cvt_f32_ubyte3_e32 v152, v198
	v_cvt_f32_ubyte3_e32 v153, v200
	v_cvt_f32_ubyte3_e32 v154, v202
	v_and_b32_e32 v155, 0xffff0000, v211
	v_and_b32_e32 v156, 0xffff0000, v215
	v_mul_f32_e32 v152, 0x3b808081, v152
	v_mul_f32_e32 v153, 0x3b808081, v153
	v_mul_f32_e32 v154, 0x3b808081, v154
	v_mul_f32_e32 v157, v152, v155
	v_fmac_f32_e32 v157, v153, v156
	v_fma_f32 v89, v154, v89, v157
	v_cvt_f32_ubyte0_e32 v152, v199
	v_cvt_f32_ubyte0_e32 v153, v201
	v_cvt_f32_ubyte0_e32 v154, v203
	v_lshlrev_b32_e32 v155, 16, v212
	v_lshlrev_b32_e32 v156, 16, v216
	v_mul_f32_e32 v152, 0x3b808081, v152
	v_mul_f32_e32 v153, 0x3b808081, v153
	v_mul_f32_e32 v154, 0x3b808081, v154
	v_mul_f32_e32 v157, v152, v155
	v_fmac_f32_e32 v157, v153, v156
	v_fma_f32 v82, v154, v82, v157
	v_cvt_f32_ubyte1_e32 v152, v199
	v_cvt_f32_ubyte1_e32 v153, v201
	v_cvt_f32_ubyte1_e32 v154, v203
	v_and_b32_e32 v155, 0xffff0000, v212
	v_and_b32_e32 v156, 0xffff0000, v216
	v_mul_f32_e32 v152, 0x3b808081, v152
	v_mul_f32_e32 v153, 0x3b808081, v153
	v_mul_f32_e32 v154, 0x3b808081, v154
	v_mul_f32_e32 v157, v152, v155
	v_fmac_f32_e32 v157, v153, v156
	v_fma_f32 v83, v154, v83, v157
	v_cvt_f32_ubyte2_e32 v152, v199
	v_cvt_f32_ubyte2_e32 v153, v201
	v_cvt_f32_ubyte2_e32 v154, v203
	v_lshlrev_b32_e32 v155, 16, v213
	v_lshlrev_b32_e32 v156, 16, v217
	v_mul_f32_e32 v152, 0x3b808081, v152
	v_mul_f32_e32 v153, 0x3b808081, v153
	v_mul_f32_e32 v154, 0x3b808081, v154
	v_mul_f32_e32 v157, v152, v155
	v_fmac_f32_e32 v157, v153, v156
	v_fma_f32 v84, v154, v84, v157
	v_cvt_f32_ubyte3_e32 v152, v199
	v_cvt_f32_ubyte3_e32 v153, v201
	v_cvt_f32_ubyte3_e32 v154, v203
	v_and_b32_e32 v155, 0xffff0000, v213
	v_and_b32_e32 v156, 0xffff0000, v217
	v_mul_f32_e32 v152, 0x3b808081, v152
	v_mul_f32_e32 v153, 0x3b808081, v153
	v_mul_f32_e32 v154, 0x3b808081, v154
	v_mul_f32_e32 v157, v152, v155
	v_fmac_f32_e32 v157, v153, v156
	v_fma_f32 v85, v154, v85, v157
	v_cvt_pk_bf16_f32 v86, v86, v87
	v_cvt_pk_bf16_f32 v87, v88, v89
	v_cvt_pk_bf16_f32 v88, v82, v83
	v_cvt_pk_bf16_f32 v89, v84, v85
	global_store_dwordx4 v149, v[86:89], s[62:63]
	s_waitcnt lgkmcnt(0)
	v_cvt_f32_ubyte0_e32 v152, v204
	v_cvt_f32_ubyte0_e32 v153, v206
	v_cvt_f32_ubyte0_e32 v154, v208
	v_lshlrev_b32_e32 v155, 16, v218
	v_lshlrev_b32_e32 v156, 16, v222
	v_mul_f32_e32 v152, 0x3b808081, v152
	v_mul_f32_e32 v153, 0x3b808081, v153
	v_mul_f32_e32 v154, 0x3b808081, v154
	v_mul_f32_e32 v157, v152, v155
	v_fmac_f32_e32 v157, v153, v156
	v_fma_f32 v70, v154, v70, v157
	v_cvt_f32_ubyte1_e32 v152, v204
	v_cvt_f32_ubyte1_e32 v153, v206
	v_cvt_f32_ubyte1_e32 v154, v208
	v_and_b32_e32 v155, 0xffff0000, v218
	v_and_b32_e32 v156, 0xffff0000, v222
	v_mul_f32_e32 v152, 0x3b808081, v152
	v_mul_f32_e32 v153, 0x3b808081, v153
	v_mul_f32_e32 v154, 0x3b808081, v154
	v_mul_f32_e32 v157, v152, v155
	v_fmac_f32_e32 v157, v153, v156
	v_fma_f32 v71, v154, v71, v157
	v_cvt_f32_ubyte2_e32 v152, v204
	v_cvt_f32_ubyte2_e32 v153, v206
	v_cvt_f32_ubyte2_e32 v154, v208
	v_lshlrev_b32_e32 v155, 16, v219
	v_lshlrev_b32_e32 v156, 16, v223
	v_mul_f32_e32 v152, 0x3b808081, v152
	v_mul_f32_e32 v153, 0x3b808081, v153
	v_mul_f32_e32 v154, 0x3b808081, v154
	v_mul_f32_e32 v157, v152, v155
	v_fmac_f32_e32 v157, v153, v156
	v_fma_f32 v72, v154, v72, v157
	v_cvt_f32_ubyte3_e32 v152, v204
	v_cvt_f32_ubyte3_e32 v153, v206
	v_cvt_f32_ubyte3_e32 v154, v208
	v_and_b32_e32 v155, 0xffff0000, v219
	v_and_b32_e32 v156, 0xffff0000, v223
	v_mul_f32_e32 v152, 0x3b808081, v152
	v_mul_f32_e32 v153, 0x3b808081, v153
	v_mul_f32_e32 v154, 0x3b808081, v154
	v_mul_f32_e32 v157, v152, v155
	v_fmac_f32_e32 v157, v153, v156
	v_fma_f32 v73, v154, v73, v157
	v_cvt_f32_ubyte0_e32 v152, v205
	v_cvt_f32_ubyte0_e32 v153, v207
	v_cvt_f32_ubyte0_e32 v154, v209
	v_lshlrev_b32_e32 v155, 16, v220
	v_lshlrev_b32_e32 v156, 16, v224
	v_mul_f32_e32 v152, 0x3b808081, v152
	v_mul_f32_e32 v153, 0x3b808081, v153
	v_mul_f32_e32 v154, 0x3b808081, v154
	v_mul_f32_e32 v157, v152, v155
	v_fmac_f32_e32 v157, v153, v156
	v_fma_f32 v66, v154, v66, v157
	v_cvt_f32_ubyte1_e32 v152, v205
	v_cvt_f32_ubyte1_e32 v153, v207
	v_cvt_f32_ubyte1_e32 v154, v209
	v_and_b32_e32 v155, 0xffff0000, v220
	v_and_b32_e32 v156, 0xffff0000, v224
	v_mul_f32_e32 v152, 0x3b808081, v152
	v_mul_f32_e32 v153, 0x3b808081, v153
	v_mul_f32_e32 v154, 0x3b808081, v154
	v_mul_f32_e32 v157, v152, v155
	v_fmac_f32_e32 v157, v153, v156
	v_fma_f32 v67, v154, v67, v157
	v_cvt_f32_ubyte2_e32 v152, v205
	v_cvt_f32_ubyte2_e32 v153, v207
; __device__ __forceinline__ void unpack8(const u32x4 w, float* f) { f[0] = bflo(w.x); f[1] = bfhi(w.x); f[2] = bflo(w.y); f[3] = bfhi(w.y); f[4] = bflo(w.z); f[5] = bfhi(w.z); f[6] = bflo(w.w); f[7] = bfhi(w.w); }
; __device__ __forceinline__ u32x4 pack8(const float* f) { u32x4 w; w.x = cvt_pk(f[0], f[1]); w.y = cvt_pk(f[2], f[3]); w.z = cvt_pk(f[4], f[5]); w.w = cvt_pk(f[6], f[7]); return w; }
;     __device__ __forceinline__ void operator()(const f32x4 (&acc)[2][2][4][2], const UnitD& u, int wr, int wc, int fr, int fq) const {
;     ...
;             for (int ai = 0; ai < 2; ++ai)
; #pragma unroll
;                 for (int m = 0; m < 4; ++m) { const int row = row0 + ai * HALF + m * 16;
;                     const unsigned char* gp = (const unsigned char*)(proj + (size_t)row * NP + C_G) + col0; const size_t po = (size_t)row * 2048 + col0;
;                     u32x2 g0[2], g1[2], g2[2]; u32x4 a[2], b[2];
; #pragma unroll
;                     for (int bj = 0; bj < 2; ++bj) { g0[bj] = *(const u32x2*)(gp + bj * HALF); g1[bj] = *(const u32x2*)(gp + 2048 + bj * HALF); g2[bj] = *(const u32x2*)(gp + 4096 + bj * HALF);
;                         a[bj] = *(const u32x4*)(PA + po + bj * HALF); b[bj] = *(const u32x4*)(PB + po + bj * HALF); }
; #pragma unroll
;                     for (int bj = 0; bj < 2; ++bj) { float f0[8], f1[8], f2[8], fa[8], fb[8], o[8];
;                         unpack_u8(g0[bj], f0); unpack_u8(g1[bj], f1); unpack_u8(g2[bj], f2); unpack8(a[bj], fa); unpack8(b[bj], fb);
;                         const f32x4 v0 = acc[ai][bj][m][0], v1 = acc[ai][bj][m][1];
; #pragma unroll
;                         for (int j = 0; j < 4; ++j) { o[j] = f0[j] * fa[j] + f1[j] * fb[j] + f2[j] * v0[j]; o[4 + j] = f0[4 + j] * fa[4 + j] + f1[4 + j] * fb[4 + j] + f2[4 + j] * v1[j]; }
;                         *(u32x4*)(H + po + bj * HALF) = pack8(o); } }
	v_cvt_f32_ubyte2_e32 v154, v209
	v_lshlrev_b32_e32 v155, 16, v221
	v_lshlrev_b32_e32 v156, 16, v225
	v_mul_f32_e32 v152, 0x3b808081, v152
	v_mul_f32_e32 v153, 0x3b808081, v153
	v_mul_f32_e32 v154, 0x3b808081, v154
	v_mul_f32_e32 v157, v152, v155
	v_fmac_f32_e32 v157, v153, v156
	v_fma_f32 v68, v154, v68, v157
	v_cvt_f32_ubyte3_e32 v152, v205
	v_cvt_f32_ubyte3_e32 v153, v207
	v_cvt_f32_ubyte3_e32 v154, v209
	v_and_b32_e32 v155, 0xffff0000, v221
	v_and_b32_e32 v156, 0xffff0000, v225
	v_mul_f32_e32 v152, 0x3b808081, v152
	v_mul_f32_e32 v153, 0x3b808081, v153
	v_mul_f32_e32 v154, 0x3b808081, v154
	v_mul_f32_e32 v157, v152, v155
	v_fmac_f32_e32 v157, v153, v156
	v_fma_f32 v69, v154, v69, v157
	v_cvt_pk_bf16_f32 v70, v70, v71
	v_cvt_pk_bf16_f32 v71, v72, v73
	v_cvt_pk_bf16_f32 v72, v66, v67
	v_cvt_pk_bf16_f32 v73, v68, v69
	global_store_dwordx4 v149, v[70:73], s[62:63] offset:256
	v_add_u32_e32 v147, 0x12000, v145
	v_add_u32_e32 v148, 0x492000, v146
	global_load_dwordx2 v[198:199], v148, s[20:21] offset:-2048
	global_load_dwordx2 v[200:201], v148, s[20:21]
	global_load_dwordx2 v[202:203], v148, s[20:21] offset:2048
	global_load_dwordx2 v[204:205], v148, s[20:21] offset:-1920
	global_load_dwordx2 v[206:207], v148, s[20:21] offset:128
	global_load_dwordx2 v[208:209], v148, s[20:21] offset:2176
	global_load_dwordx4 v[210:213], v147, s[58:59]
	global_load_dwordx4 v[214:217], v147, s[60:61]
	global_load_dwordx4 v[218:221], v147, s[58:59] offset:256
	global_load_dwordx4 v[222:225], v147, s[60:61] offset:256
	ds_write_b128 v251, v[62:65]
	ds_read_b128 v[62:65], v252
	ds_write_b128 v251, v[58:61]
	ds_read_b128 v[58:61], v252
	ds_write_b128 v251, v[46:49]
	ds_read_b128 v[46:49], v252
	ds_write_b128 v251, v[42:45]
	ds_read_b128 v[42:45], v252
	v_add_u32_e32 v149, 0x80000, v151
	s_waitcnt vmcnt(12)
	s_waitcnt lgkmcnt(4)
	v_cvt_f32_ubyte0_e32 v152, v130
	v_cvt_f32_ubyte0_e32 v153, v132
	v_cvt_f32_ubyte0_e32 v154, v134
	v_lshlrev_b32_e32 v155, 16, v164
	v_lshlrev_b32_e32 v156, 16, v168
	v_mul_f32_e32 v152, 0x3b808081, v152
	v_mul_f32_e32 v153, 0x3b808081, v153
	v_mul_f32_e32 v154, 0x3b808081, v154
	v_mul_f32_e32 v157, v152, v155
	v_fmac_f32_e32 v157, v153, v156
	v_fma_f32 v62, v154, v62, v157
	v_cvt_f32_ubyte1_e32 v152, v130
	v_cvt_f32_ubyte1_e32 v153, v132
	v_cvt_f32_ubyte1_e32 v154, v134
	v_and_b32_e32 v155, 0xffff0000, v164
	v_and_b32_e32 v156, 0xffff0000, v168
	v_mul_f32_e32 v152, 0x3b808081, v152
	v_mul_f32_e32 v153, 0x3b808081, v153
	v_mul_f32_e32 v154, 0x3b808081, v154
	v_mul_f32_e32 v157, v152, v155
	v_fmac_f32_e32 v157, v153, v156
	v_fma_f32 v63, v154, v63, v157
	v_cvt_f32_ubyte2_e32 v152, v130
	v_cvt_f32_ubyte2_e32 v153, v132
	v_cvt_f32_ubyte2_e32 v154, v134
	v_lshlrev_b32_e32 v155, 16, v165
	v_lshlrev_b32_e32 v156, 16, v169
	v_mul_f32_e32 v152, 0x3b808081, v152
	v_mul_f32_e32 v153, 0x3b808081, v153
	v_mul_f32_e32 v154, 0x3b808081, v154
	v_mul_f32_e32 v157, v152, v155
	v_fmac_f32_e32 v157, v153, v156
	v_fma_f32 v64, v154, v64, v157
	v_cvt_f32_ubyte3_e32 v152, v130
	v_cvt_f32_ubyte3_e32 v153, v132
	v_cvt_f32_ubyte3_e32 v154, v134
	v_and_b32_e32 v155, 0xffff0000, v165
	v_and_b32_e32 v156, 0xffff0000, v169
	v_mul_f32_e32 v152, 0x3b808081, v152
	v_mul_f32_e32 v153, 0x3b808081, v153
	v_mul_f32_e32 v154, 0x3b808081, v154
	v_mul_f32_e32 v157, v152, v155
	v_fmac_f32_e32 v157, v153, v156
	v_fma_f32 v65, v154, v65, v157
	v_cvt_f32_ubyte0_e32 v152, v131
	v_cvt_f32_ubyte0_e32 v153, v133
	v_cvt_f32_ubyte0_e32 v154, v135
	v_lshlrev_b32_e32 v155, 16, v166
	v_lshlrev_b32_e32 v156, 16, v170
	v_mul_f32_e32 v152, 0x3b808081, v152
	v_mul_f32_e32 v153, 0x3b808081, v153
	v_mul_f32_e32 v154, 0x3b808081, v154
	v_mul_f32_e32 v157, v152, v155
	v_fmac_f32_e32 v157, v153, v156
	v_fma_f32 v58, v154, v58, v157
	v_cvt_f32_ubyte1_e32 v152, v131
	v_cvt_f32_ubyte1_e32 v153, v133
	v_cvt_f32_ubyte1_e32 v154, v135
	v_and_b32_e32 v155, 0xffff0000, v166
	v_and_b32_e32 v156, 0xffff0000, v170
	v_mul_f32_e32 v152, 0x3b808081, v152
	v_mul_f32_e32 v153, 0x3b808081, v153
	v_mul_f32_e32 v154, 0x3b808081, v154
	v_mul_f32_e32 v157, v152, v155
	v_fmac_f32_e32 v157, v153, v156
	v_fma_f32 v59, v154, v59, v157
	v_cvt_f32_ubyte2_e32 v152, v131
	v_cvt_f32_ubyte2_e32 v153, v133
	v_cvt_f32_ubyte2_e32 v154, v135
	v_lshlrev_b32_e32 v155, 16, v167
	v_lshlrev_b32_e32 v156, 16, v171
	v_mul_f32_e32 v152, 0x3b808081, v152
	v_mul_f32_e32 v153, 0x3b808081, v153
	v_mul_f32_e32 v154, 0x3b808081, v154
	v_mul_f32_e32 v157, v152, v155
	v_fmac_f32_e32 v157, v153, v156
	v_fma_f32 v60, v154, v60, v157
	v_cvt_f32_ubyte3_e32 v152, v131
	v_cvt_f32_ubyte3_e32 v153, v133
	v_cvt_f32_ubyte3_e32 v154, v135
	v_and_b32_e32 v155, 0xffff0000, v167
	v_and_b32_e32 v156, 0xffff0000, v171
	v_mul_f32_e32 v152, 0x3b808081, v152
	v_mul_f32_e32 v153, 0x3b808081, v153
	v_mul_f32_e32 v154, 0x3b808081, v154
	v_mul_f32_e32 v157, v152, v155
	v_fmac_f32_e32 v157, v153, v156
	v_fma_f32 v61, v154, v61, v157
	v_cvt_pk_bf16_f32 v62, v62, v63
	v_cvt_pk_bf16_f32 v63, v64, v65
	v_cvt_pk_bf16_f32 v64, v58, v59
	v_cvt_pk_bf16_f32 v65, v60, v61
	global_store_dwordx4 v149, v[62:65], s[62:63]
	s_waitcnt lgkmcnt(0)
; __device__ __forceinline__ void unpack8(const u32x4 w, float* f) { f[0] = bflo(w.x); f[1] = bfhi(w.x); f[2] = bflo(w.y); f[3] = bfhi(w.y); f[4] = bflo(w.z); f[5] = bfhi(w.z); f[6] = bflo(w.w); f[7] = bfhi(w.w); }
; __device__ __forceinline__ u32x4 pack8(const float* f) { u32x4 w; w.x = cvt_pk(f[0], f[1]); w.y = cvt_pk(f[2], f[3]); w.z = cvt_pk(f[4], f[5]); w.w = cvt_pk(f[6], f[7]); return w; }
;     __device__ __forceinline__ void operator()(const f32x4 (&acc)[2][2][4][2], const UnitD& u, int wr, int wc, int fr, int fq) const {
;     ...
;             for (int ai = 0; ai < 2; ++ai)
; #pragma unroll
;                 for (int m = 0; m < 4; ++m) { const int row = row0 + ai * HALF + m * 16;
;                     const unsigned char* gp = (const unsigned char*)(proj + (size_t)row * NP + C_G) + col0; const size_t po = (size_t)row * 2048 + col0;
;                     u32x2 g0[2], g1[2], g2[2]; u32x4 a[2], b[2];
; #pragma unroll
;                     for (int bj = 0; bj < 2; ++bj) { g0[bj] = *(const u32x2*)(gp + bj * HALF); g1[bj] = *(const u32x2*)(gp + 2048 + bj * HALF); g2[bj] = *(const u32x2*)(gp + 4096 + bj * HALF);
;                         a[bj] = *(const u32x4*)(PA + po + bj * HALF); b[bj] = *(const u32x4*)(PB + po + bj * HALF); }
; #pragma unroll
;                     for (int bj = 0; bj < 2; ++bj) { float f0[8], f1[8], f2[8], fa[8], fb[8], o[8];
;                         unpack_u8(g0[bj], f0); unpack_u8(g1[bj], f1); unpack_u8(g2[bj], f2); unpack8(a[bj], fa); unpack8(b[bj], fb);
;                         const f32x4 v0 = acc[ai][bj][m][0], v1 = acc[ai][bj][m][1];
; #pragma unroll
;                         for (int j = 0; j < 4; ++j) { o[j] = f0[j] * fa[j] + f1[j] * fb[j] + f2[j] * v0[j]; o[4 + j] = f0[4 + j] * fa[4 + j] + f1[4 + j] * fb[4 + j] + f2[4 + j] * v1[j]; }
;                         *(u32x4*)(H + po + bj * HALF) = pack8(o); } }
	v_cvt_f32_ubyte0_e32 v152, v136
	v_cvt_f32_ubyte0_e32 v153, v160
	v_cvt_f32_ubyte0_e32 v154, v162
	v_lshlrev_b32_e32 v155, 16, v172
	v_lshlrev_b32_e32 v156, 16, v176
	v_mul_f32_e32 v152, 0x3b808081, v152
	v_mul_f32_e32 v153, 0x3b808081, v153
	v_mul_f32_e32 v154, 0x3b808081, v154
	v_mul_f32_e32 v157, v152, v155
	v_fmac_f32_e32 v157, v153, v156
	v_fma_f32 v46, v154, v46, v157
	v_cvt_f32_ubyte1_e32 v152, v136
	v_cvt_f32_ubyte1_e32 v153, v160
	v_cvt_f32_ubyte1_e32 v154, v162
	v_and_b32_e32 v155, 0xffff0000, v172
	v_and_b32_e32 v156, 0xffff0000, v176
	v_mul_f32_e32 v152, 0x3b808081, v152
	v_mul_f32_e32 v153, 0x3b808081, v153
	v_mul_f32_e32 v154, 0x3b808081, v154
	v_mul_f32_e32 v157, v152, v155
	v_fmac_f32_e32 v157, v153, v156
	v_fma_f32 v47, v154, v47, v157
	v_cvt_f32_ubyte2_e32 v152, v136
	v_cvt_f32_ubyte2_e32 v153, v160
	v_cvt_f32_ubyte2_e32 v154, v162
	v_lshlrev_b32_e32 v155, 16, v173
	v_lshlrev_b32_e32 v156, 16, v177
	v_mul_f32_e32 v152, 0x3b808081, v152
	v_mul_f32_e32 v153, 0x3b808081, v153
	v_mul_f32_e32 v154, 0x3b808081, v154
	v_mul_f32_e32 v157, v152, v155
	v_fmac_f32_e32 v157, v153, v156
	v_fma_f32 v48, v154, v48, v157
	v_cvt_f32_ubyte3_e32 v152, v136
	v_cvt_f32_ubyte3_e32 v153, v160
	v_cvt_f32_ubyte3_e32 v154, v162
	v_and_b32_e32 v155, 0xffff0000, v173
	v_and_b32_e32 v156, 0xffff0000, v177
	v_mul_f32_e32 v152, 0x3b808081, v152
	v_mul_f32_e32 v153, 0x3b808081, v153
	v_mul_f32_e32 v154, 0x3b808081, v154
	v_mul_f32_e32 v157, v152, v155
	v_fmac_f32_e32 v157, v153, v156
	v_fma_f32 v49, v154, v49, v157
	v_cvt_f32_ubyte0_e32 v152, v137
	v_cvt_f32_ubyte0_e32 v153, v161
	v_cvt_f32_ubyte0_e32 v154, v163
	v_lshlrev_b32_e32 v155, 16, v174
	v_lshlrev_b32_e32 v156, 16, v178
	v_mul_f32_e32 v152, 0x3b808081, v152
	v_mul_f32_e32 v153, 0x3b808081, v153
	v_mul_f32_e32 v154, 0x3b808081, v154
	v_mul_f32_e32 v157, v152, v155
	v_fmac_f32_e32 v157, v153, v156
	v_fma_f32 v42, v154, v42, v157
	v_cvt_f32_ubyte1_e32 v152, v137
	v_cvt_f32_ubyte1_e32 v153, v161
	v_cvt_f32_ubyte1_e32 v154, v163
	v_and_b32_e32 v155, 0xffff0000, v174
	v_and_b32_e32 v156, 0xffff0000, v178
	v_mul_f32_e32 v152, 0x3b808081, v152
	v_mul_f32_e32 v153, 0x3b808081, v153
	v_mul_f32_e32 v154, 0x3b808081, v154
	v_mul_f32_e32 v157, v152, v155
	v_fmac_f32_e32 v157, v153, v156
	v_fma_f32 v43, v154, v43, v157
	v_cvt_f32_ubyte2_e32 v152, v137
	v_cvt_f32_ubyte2_e32 v153, v161
	v_cvt_f32_ubyte2_e32 v154, v163
	v_lshlrev_b32_e32 v155, 16, v175
	v_lshlrev_b32_e32 v156, 16, v179
	v_mul_f32_e32 v152, 0x3b808081, v152
	v_mul_f32_e32 v153, 0x3b808081, v153
	v_mul_f32_e32 v154, 0x3b808081, v154
	v_mul_f32_e32 v157, v152, v155
	v_fmac_f32_e32 v157, v153, v156
	v_fma_f32 v44, v154, v44, v157
	v_cvt_f32_ubyte3_e32 v152, v137
	v_cvt_f32_ubyte3_e32 v153, v161
	v_cvt_f32_ubyte3_e32 v154, v163
	v_and_b32_e32 v155, 0xffff0000, v175
	v_and_b32_e32 v156, 0xffff0000, v179
	v_mul_f32_e32 v152, 0x3b808081, v152
	v_mul_f32_e32 v153, 0x3b808081, v153
	v_mul_f32_e32 v154, 0x3b808081, v154
	v_mul_f32_e32 v157, v152, v155
	v_fmac_f32_e32 v157, v153, v156
	v_fma_f32 v45, v154, v45, v157
	v_cvt_pk_bf16_f32 v46, v46, v47
	v_cvt_pk_bf16_f32 v47, v48, v49
	v_cvt_pk_bf16_f32 v48, v42, v43
	v_cvt_pk_bf16_f32 v49, v44, v45
	global_store_dwordx4 v149, v[46:49], s[62:63] offset:256
	v_add_u32_e32 v147, 0x14000, v145
	v_add_u32_e32 v148, 0x514000, v146
	global_load_dwordx2 v[130:131], v148, s[20:21] offset:-2048
	global_load_dwordx2 v[132:133], v148, s[20:21]
	global_load_dwordx2 v[134:135], v148, s[20:21] offset:2048
	global_load_dwordx2 v[136:137], v148, s[20:21] offset:-1920
	global_load_dwordx2 v[160:161], v148, s[20:21] offset:128
	global_load_dwordx2 v[162:163], v148, s[20:21] offset:2176
	global_load_dwordx4 v[164:167], v147, s[58:59]
	global_load_dwordx4 v[168:171], v147, s[60:61]
	global_load_dwordx4 v[172:175], v147, s[58:59] offset:256
	global_load_dwordx4 v[176:179], v147, s[60:61] offset:256
	ds_write_b128 v251, v[54:57]
	ds_read_b128 v[54:57], v252
	ds_write_b128 v251, v[50:53]
	ds_read_b128 v[50:53], v252
	ds_write_b128 v251, v[30:33]
	ds_read_b128 v[30:33], v252
	ds_write_b128 v251, v[26:29]
	ds_read_b128 v[26:29], v252
	v_add_u32_e32 v149, 0x90000, v151
	s_waitcnt vmcnt(12)
	s_waitcnt lgkmcnt(4)
	v_cvt_f32_ubyte0_e32 v152, v198
	v_cvt_f32_ubyte0_e32 v153, v200
	v_cvt_f32_ubyte0_e32 v154, v202
	v_lshlrev_b32_e32 v155, 16, v210
	v_lshlrev_b32_e32 v156, 16, v214
	v_mul_f32_e32 v152, 0x3b808081, v152
	v_mul_f32_e32 v153, 0x3b808081, v153
	v_mul_f32_e32 v154, 0x3b808081, v154
	v_mul_f32_e32 v157, v152, v155
	v_fmac_f32_e32 v157, v153, v156
	v_fma_f32 v54, v154, v54, v157
	v_cvt_f32_ubyte1_e32 v152, v198
	v_cvt_f32_ubyte1_e32 v153, v200
	v_cvt_f32_ubyte1_e32 v154, v202
	v_and_b32_e32 v155, 0xffff0000, v210
	v_and_b32_e32 v156, 0xffff0000, v214
	v_mul_f32_e32 v152, 0x3b808081, v152
	v_mul_f32_e32 v153, 0x3b808081, v153
	v_mul_f32_e32 v154, 0x3b808081, v154
	v_mul_f32_e32 v157, v152, v155
	v_fmac_f32_e32 v157, v153, v156
	v_fma_f32 v55, v154, v55, v157
	v_cvt_f32_ubyte2_e32 v152, v198
	v_cvt_f32_ubyte2_e32 v153, v200
	v_cvt_f32_ubyte2_e32 v154, v202
	v_lshlrev_b32_e32 v155, 16, v211
	v_lshlrev_b32_e32 v156, 16, v215
	v_mul_f32_e32 v152, 0x3b808081, v152
	v_mul_f32_e32 v153, 0x3b808081, v153
	v_mul_f32_e32 v154, 0x3b808081, v154
	v_mul_f32_e32 v157, v152, v155
	v_fmac_f32_e32 v157, v153, v156
	v_fma_f32 v56, v154, v56, v157
	v_cvt_f32_ubyte3_e32 v152, v198
	v_cvt_f32_ubyte3_e32 v153, v200
	v_cvt_f32_ubyte3_e32 v154, v202
	v_and_b32_e32 v155, 0xffff0000, v211
	v_and_b32_e32 v156, 0xffff0000, v215
	v_mul_f32_e32 v152, 0x3b808081, v152
	v_mul_f32_e32 v153, 0x3b808081, v153
	v_mul_f32_e32 v154, 0x3b808081, v154
; __device__ __forceinline__ void unpack8(const u32x4 w, float* f) { f[0] = bflo(w.x); f[1] = bfhi(w.x); f[2] = bflo(w.y); f[3] = bfhi(w.y); f[4] = bflo(w.z); f[5] = bfhi(w.z); f[6] = bflo(w.w); f[7] = bfhi(w.w); }
; __device__ __forceinline__ u32x4 pack8(const float* f) { u32x4 w; w.x = cvt_pk(f[0], f[1]); w.y = cvt_pk(f[2], f[3]); w.z = cvt_pk(f[4], f[5]); w.w = cvt_pk(f[6], f[7]); return w; }
;     __device__ __forceinline__ void operator()(const f32x4 (&acc)[2][2][4][2], const UnitD& u, int wr, int wc, int fr, int fq) const {
;     ...
;             for (int ai = 0; ai < 2; ++ai)
; #pragma unroll
;                 for (int m = 0; m < 4; ++m) { const int row = row0 + ai * HALF + m * 16;
;                     const unsigned char* gp = (const unsigned char*)(proj + (size_t)row * NP + C_G) + col0; const size_t po = (size_t)row * 2048 + col0;
;                     u32x2 g0[2], g1[2], g2[2]; u32x4 a[2], b[2];
; #pragma unroll
;                     for (int bj = 0; bj < 2; ++bj) { g0[bj] = *(const u32x2*)(gp + bj * HALF); g1[bj] = *(const u32x2*)(gp + 2048 + bj * HALF); g2[bj] = *(const u32x2*)(gp + 4096 + bj * HALF);
;                         a[bj] = *(const u32x4*)(PA + po + bj * HALF); b[bj] = *(const u32x4*)(PB + po + bj * HALF); }
; #pragma unroll
;                     for (int bj = 0; bj < 2; ++bj) { float f0[8], f1[8], f2[8], fa[8], fb[8], o[8];
;                         unpack_u8(g0[bj], f0); unpack_u8(g1[bj], f1); unpack_u8(g2[bj], f2); unpack8(a[bj], fa); unpack8(b[bj], fb);
;                         const f32x4 v0 = acc[ai][bj][m][0], v1 = acc[ai][bj][m][1];
; #pragma unroll
;                         for (int j = 0; j < 4; ++j) { o[j] = f0[j] * fa[j] + f1[j] * fb[j] + f2[j] * v0[j]; o[4 + j] = f0[4 + j] * fa[4 + j] + f1[4 + j] * fb[4 + j] + f2[4 + j] * v1[j]; }
;                         *(u32x4*)(H + po + bj * HALF) = pack8(o); } }
	v_mul_f32_e32 v157, v152, v155
	v_fmac_f32_e32 v157, v153, v156
	v_fma_f32 v57, v154, v57, v157
	v_cvt_f32_ubyte0_e32 v152, v199
	v_cvt_f32_ubyte0_e32 v153, v201
	v_cvt_f32_ubyte0_e32 v154, v203
	v_lshlrev_b32_e32 v155, 16, v212
	v_lshlrev_b32_e32 v156, 16, v216
	v_mul_f32_e32 v152, 0x3b808081, v152
	v_mul_f32_e32 v153, 0x3b808081, v153
	v_mul_f32_e32 v154, 0x3b808081, v154
	v_mul_f32_e32 v157, v152, v155
	v_fmac_f32_e32 v157, v153, v156
	v_fma_f32 v50, v154, v50, v157
	v_cvt_f32_ubyte1_e32 v152, v199
	v_cvt_f32_ubyte1_e32 v153, v201
	v_cvt_f32_ubyte1_e32 v154, v203
	v_and_b32_e32 v155, 0xffff0000, v212
	v_and_b32_e32 v156, 0xffff0000, v216
	v_mul_f32_e32 v152, 0x3b808081, v152
	v_mul_f32_e32 v153, 0x3b808081, v153
	v_mul_f32_e32 v154, 0x3b808081, v154
	v_mul_f32_e32 v157, v152, v155
	v_fmac_f32_e32 v157, v153, v156
	v_fma_f32 v51, v154, v51, v157
	v_cvt_f32_ubyte2_e32 v152, v199
	v_cvt_f32_ubyte2_e32 v153, v201
	v_cvt_f32_ubyte2_e32 v154, v203
	v_lshlrev_b32_e32 v155, 16, v213
	v_lshlrev_b32_e32 v156, 16, v217
	v_mul_f32_e32 v152, 0x3b808081, v152
	v_mul_f32_e32 v153, 0x3b808081, v153
	v_mul_f32_e32 v154, 0x3b808081, v154
	v_mul_f32_e32 v157, v152, v155
	v_fmac_f32_e32 v157, v153, v156
	v_fma_f32 v52, v154, v52, v157
	v_cvt_f32_ubyte3_e32 v152, v199
	v_cvt_f32_ubyte3_e32 v153, v201
	v_cvt_f32_ubyte3_e32 v154, v203
	v_and_b32_e32 v155, 0xffff0000, v213
	v_and_b32_e32 v156, 0xffff0000, v217
	v_mul_f32_e32 v152, 0x3b808081, v152
	v_mul_f32_e32 v153, 0x3b808081, v153
	v_mul_f32_e32 v154, 0x3b808081, v154
	v_mul_f32_e32 v157, v152, v155
	v_fmac_f32_e32 v157, v153, v156
	v_fma_f32 v53, v154, v53, v157
	v_cvt_pk_bf16_f32 v54, v54, v55
	v_cvt_pk_bf16_f32 v55, v56, v57
	v_cvt_pk_bf16_f32 v56, v50, v51
	v_cvt_pk_bf16_f32 v57, v52, v53
	global_store_dwordx4 v149, v[54:57], s[62:63]
	s_waitcnt lgkmcnt(0)
	v_cvt_f32_ubyte0_e32 v152, v204
	v_cvt_f32_ubyte0_e32 v153, v206
	v_cvt_f32_ubyte0_e32 v154, v208
	v_lshlrev_b32_e32 v155, 16, v218
	v_lshlrev_b32_e32 v156, 16, v222
	v_mul_f32_e32 v152, 0x3b808081, v152
	v_mul_f32_e32 v153, 0x3b808081, v153
	v_mul_f32_e32 v154, 0x3b808081, v154
	v_mul_f32_e32 v157, v152, v155
	v_fmac_f32_e32 v157, v153, v156
	v_fma_f32 v30, v154, v30, v157
	v_cvt_f32_ubyte1_e32 v152, v204
	v_cvt_f32_ubyte1_e32 v153, v206
	v_cvt_f32_ubyte1_e32 v154, v208
	v_and_b32_e32 v155, 0xffff0000, v218
	v_and_b32_e32 v156, 0xffff0000, v222
	v_mul_f32_e32 v152, 0x3b808081, v152
	v_mul_f32_e32 v153, 0x3b808081, v153
	v_mul_f32_e32 v154, 0x3b808081, v154
	v_mul_f32_e32 v157, v152, v155
	v_fmac_f32_e32 v157, v153, v156
	v_fma_f32 v31, v154, v31, v157
	v_cvt_f32_ubyte2_e32 v152, v204
	v_cvt_f32_ubyte2_e32 v153, v206
	v_cvt_f32_ubyte2_e32 v154, v208
	v_lshlrev_b32_e32 v155, 16, v219
	v_lshlrev_b32_e32 v156, 16, v223
	v_mul_f32_e32 v152, 0x3b808081, v152
	v_mul_f32_e32 v153, 0x3b808081, v153
	v_mul_f32_e32 v154, 0x3b808081, v154
	v_mul_f32_e32 v157, v152, v155
	v_fmac_f32_e32 v157, v153, v156
	v_fma_f32 v32, v154, v32, v157
	v_cvt_f32_ubyte3_e32 v152, v204
	v_cvt_f32_ubyte3_e32 v153, v206
	v_cvt_f32_ubyte3_e32 v154, v208
	v_and_b32_e32 v155, 0xffff0000, v219
	v_and_b32_e32 v156, 0xffff0000, v223
	v_mul_f32_e32 v152, 0x3b808081, v152
	v_mul_f32_e32 v153, 0x3b808081, v153
	v_mul_f32_e32 v154, 0x3b808081, v154
	v_mul_f32_e32 v157, v152, v155
	v_fmac_f32_e32 v157, v153, v156
	v_fma_f32 v33, v154, v33, v157
	v_cvt_f32_ubyte0_e32 v152, v205
	v_cvt_f32_ubyte0_e32 v153, v207
	v_cvt_f32_ubyte0_e32 v154, v209
	v_lshlrev_b32_e32 v155, 16, v220
	v_lshlrev_b32_e32 v156, 16, v224
	v_mul_f32_e32 v152, 0x3b808081, v152
	v_mul_f32_e32 v153, 0x3b808081, v153
	v_mul_f32_e32 v154, 0x3b808081, v154
	v_mul_f32_e32 v157, v152, v155
	v_fmac_f32_e32 v157, v153, v156
	v_fma_f32 v26, v154, v26, v157
	v_cvt_f32_ubyte1_e32 v152, v205
	v_cvt_f32_ubyte1_e32 v153, v207
	v_cvt_f32_ubyte1_e32 v154, v209
	v_and_b32_e32 v155, 0xffff0000, v220
	v_and_b32_e32 v156, 0xffff0000, v224
	v_mul_f32_e32 v152, 0x3b808081, v152
	v_mul_f32_e32 v153, 0x3b808081, v153
	v_mul_f32_e32 v154, 0x3b808081, v154
	v_mul_f32_e32 v157, v152, v155
	v_fmac_f32_e32 v157, v153, v156
	v_fma_f32 v27, v154, v27, v157
	v_cvt_f32_ubyte2_e32 v152, v205
	v_cvt_f32_ubyte2_e32 v153, v207
	v_cvt_f32_ubyte2_e32 v154, v209
	v_lshlrev_b32_e32 v155, 16, v221
	v_lshlrev_b32_e32 v156, 16, v225
	v_mul_f32_e32 v152, 0x3b808081, v152
	v_mul_f32_e32 v153, 0x3b808081, v153
	v_mul_f32_e32 v154, 0x3b808081, v154
	v_mul_f32_e32 v157, v152, v155
	v_fmac_f32_e32 v157, v153, v156
	v_fma_f32 v28, v154, v28, v157
	v_cvt_f32_ubyte3_e32 v152, v205
	v_cvt_f32_ubyte3_e32 v153, v207
	v_cvt_f32_ubyte3_e32 v154, v209
	v_and_b32_e32 v155, 0xffff0000, v221
	v_and_b32_e32 v156, 0xffff0000, v225
	v_mul_f32_e32 v152, 0x3b808081, v152
	v_mul_f32_e32 v153, 0x3b808081, v153
	v_mul_f32_e32 v154, 0x3b808081, v154
	v_mul_f32_e32 v157, v152, v155
	v_fmac_f32_e32 v157, v153, v156
	v_fma_f32 v29, v154, v29, v157
	v_cvt_pk_bf16_f32 v30, v30, v31
	v_cvt_pk_bf16_f32 v31, v32, v33
	v_cvt_pk_bf16_f32 v32, v26, v27
	v_cvt_pk_bf16_f32 v33, v28, v29
	global_store_dwordx4 v149, v[30:33], s[62:63] offset:256
	v_add_u32_e32 v147, 0x16000, v145
	v_add_u32_e32 v148, 0x596000, v146
	global_load_dwordx2 v[198:199], v148, s[20:21] offset:-2048
	global_load_dwordx2 v[200:201], v148, s[20:21]
	global_load_dwordx2 v[202:203], v148, s[20:21] offset:2048
	global_load_dwordx2 v[204:205], v148, s[20:21] offset:-1920
	global_load_dwordx2 v[206:207], v148, s[20:21] offset:128
	global_load_dwordx2 v[208:209], v148, s[20:21] offset:2176
	global_load_dwordx4 v[210:213], v147, s[58:59]
	global_load_dwordx4 v[214:217], v147, s[60:61]
	global_load_dwordx4 v[218:221], v147, s[58:59] offset:256
	global_load_dwordx4 v[222:225], v147, s[60:61] offset:256
	ds_write_b128 v251, v[38:41]
	ds_read_b128 v[38:41], v252
	ds_write_b128 v251, v[34:37]
	ds_read_b128 v[34:37], v252
	ds_write_b128 v251, v[14:17]
	ds_read_b128 v[14:17], v252
	ds_write_b128 v251, v[10:13]
	ds_read_b128 v[10:13], v252
	v_add_u32_e32 v149, 0xa0000, v151
	s_waitcnt vmcnt(12)
; __device__ __forceinline__ void unpack8(const u32x4 w, float* f) { f[0] = bflo(w.x); f[1] = bfhi(w.x); f[2] = bflo(w.y); f[3] = bfhi(w.y); f[4] = bflo(w.z); f[5] = bfhi(w.z); f[6] = bflo(w.w); f[7] = bfhi(w.w); }
; __device__ __forceinline__ u32x4 pack8(const float* f) { u32x4 w; w.x = cvt_pk(f[0], f[1]); w.y = cvt_pk(f[2], f[3]); w.z = cvt_pk(f[4], f[5]); w.w = cvt_pk(f[6], f[7]); return w; }
;     __device__ __forceinline__ void operator()(const f32x4 (&acc)[2][2][4][2], const UnitD& u, int wr, int wc, int fr, int fq) const {
;     ...
;             for (int ai = 0; ai < 2; ++ai)
; #pragma unroll
;                 for (int m = 0; m < 4; ++m) { const int row = row0 + ai * HALF + m * 16;
;                     const unsigned char* gp = (const unsigned char*)(proj + (size_t)row * NP + C_G) + col0; const size_t po = (size_t)row * 2048 + col0;
;                     u32x2 g0[2], g1[2], g2[2]; u32x4 a[2], b[2];
; #pragma unroll
;                     for (int bj = 0; bj < 2; ++bj) { g0[bj] = *(const u32x2*)(gp + bj * HALF); g1[bj] = *(const u32x2*)(gp + 2048 + bj * HALF); g2[bj] = *(const u32x2*)(gp + 4096 + bj * HALF);
;                         a[bj] = *(const u32x4*)(PA + po + bj * HALF); b[bj] = *(const u32x4*)(PB + po + bj * HALF); }
; #pragma unroll
;                     for (int bj = 0; bj < 2; ++bj) { float f0[8], f1[8], f2[8], fa[8], fb[8], o[8];
;                         unpack_u8(g0[bj], f0); unpack_u8(g1[bj], f1); unpack_u8(g2[bj], f2); unpack8(a[bj], fa); unpack8(b[bj], fb);
;                         const f32x4 v0 = acc[ai][bj][m][0], v1 = acc[ai][bj][m][1];
; #pragma unroll
;                         for (int j = 0; j < 4; ++j) { o[j] = f0[j] * fa[j] + f1[j] * fb[j] + f2[j] * v0[j]; o[4 + j] = f0[4 + j] * fa[4 + j] + f1[4 + j] * fb[4 + j] + f2[4 + j] * v1[j]; }
;                         *(u32x4*)(H + po + bj * HALF) = pack8(o); } }
	s_waitcnt lgkmcnt(4)
	v_cvt_f32_ubyte0_e32 v152, v130
	v_cvt_f32_ubyte0_e32 v153, v132
	v_cvt_f32_ubyte0_e32 v154, v134
	v_lshlrev_b32_e32 v155, 16, v164
	v_lshlrev_b32_e32 v156, 16, v168
	v_mul_f32_e32 v152, 0x3b808081, v152
	v_mul_f32_e32 v153, 0x3b808081, v153
	v_mul_f32_e32 v154, 0x3b808081, v154
	v_mul_f32_e32 v157, v152, v155
	v_fmac_f32_e32 v157, v153, v156
	v_fma_f32 v38, v154, v38, v157
	v_cvt_f32_ubyte1_e32 v152, v130
	v_cvt_f32_ubyte1_e32 v153, v132
	v_cvt_f32_ubyte1_e32 v154, v134
	v_and_b32_e32 v155, 0xffff0000, v164
	v_and_b32_e32 v156, 0xffff0000, v168
	v_mul_f32_e32 v152, 0x3b808081, v152
	v_mul_f32_e32 v153, 0x3b808081, v153
	v_mul_f32_e32 v154, 0x3b808081, v154
	v_mul_f32_e32 v157, v152, v155
	v_fmac_f32_e32 v157, v153, v156
	v_fma_f32 v39, v154, v39, v157
	v_cvt_f32_ubyte2_e32 v152, v130
	v_cvt_f32_ubyte2_e32 v153, v132
	v_cvt_f32_ubyte2_e32 v154, v134
	v_lshlrev_b32_e32 v155, 16, v165
	v_lshlrev_b32_e32 v156, 16, v169
	v_mul_f32_e32 v152, 0x3b808081, v152
	v_mul_f32_e32 v153, 0x3b808081, v153
	v_mul_f32_e32 v154, 0x3b808081, v154
	v_mul_f32_e32 v157, v152, v155
	v_fmac_f32_e32 v157, v153, v156
	v_fma_f32 v40, v154, v40, v157
	v_cvt_f32_ubyte3_e32 v152, v130
	v_cvt_f32_ubyte3_e32 v153, v132
	v_cvt_f32_ubyte3_e32 v154, v134
	v_and_b32_e32 v155, 0xffff0000, v165
	v_and_b32_e32 v156, 0xffff0000, v169
	v_mul_f32_e32 v152, 0x3b808081, v152
	v_mul_f32_e32 v153, 0x3b808081, v153
	v_mul_f32_e32 v154, 0x3b808081, v154
	v_mul_f32_e32 v157, v152, v155
	v_fmac_f32_e32 v157, v153, v156
	v_fma_f32 v41, v154, v41, v157
	v_cvt_f32_ubyte0_e32 v152, v131
	v_cvt_f32_ubyte0_e32 v153, v133
	v_cvt_f32_ubyte0_e32 v154, v135
	v_lshlrev_b32_e32 v155, 16, v166
	v_lshlrev_b32_e32 v156, 16, v170
	v_mul_f32_e32 v152, 0x3b808081, v152
	v_mul_f32_e32 v153, 0x3b808081, v153
	v_mul_f32_e32 v154, 0x3b808081, v154
	v_mul_f32_e32 v157, v152, v155
	v_fmac_f32_e32 v157, v153, v156
	v_fma_f32 v34, v154, v34, v157
	v_cvt_f32_ubyte1_e32 v152, v131
	v_cvt_f32_ubyte1_e32 v153, v133
	v_cvt_f32_ubyte1_e32 v154, v135
	v_and_b32_e32 v155, 0xffff0000, v166
	v_and_b32_e32 v156, 0xffff0000, v170
	v_mul_f32_e32 v152, 0x3b808081, v152
	v_mul_f32_e32 v153, 0x3b808081, v153
	v_mul_f32_e32 v154, 0x3b808081, v154
	v_mul_f32_e32 v157, v152, v155
	v_fmac_f32_e32 v157, v153, v156
	v_fma_f32 v35, v154, v35, v157
	v_cvt_f32_ubyte2_e32 v152, v131
	v_cvt_f32_ubyte2_e32 v153, v133
	v_cvt_f32_ubyte2_e32 v154, v135
	v_lshlrev_b32_e32 v155, 16, v167
	v_lshlrev_b32_e32 v156, 16, v171
	v_mul_f32_e32 v152, 0x3b808081, v152
	v_mul_f32_e32 v153, 0x3b808081, v153
	v_mul_f32_e32 v154, 0x3b808081, v154
	v_mul_f32_e32 v157, v152, v155
	v_fmac_f32_e32 v157, v153, v156
	v_fma_f32 v36, v154, v36, v157
	v_cvt_f32_ubyte3_e32 v152, v131
	v_cvt_f32_ubyte3_e32 v153, v133
	v_cvt_f32_ubyte3_e32 v154, v135
	v_and_b32_e32 v155, 0xffff0000, v167
	v_and_b32_e32 v156, 0xffff0000, v171
	v_mul_f32_e32 v152, 0x3b808081, v152
	v_mul_f32_e32 v153, 0x3b808081, v153
	v_mul_f32_e32 v154, 0x3b808081, v154
	v_mul_f32_e32 v157, v152, v155
	v_fmac_f32_e32 v157, v153, v156
	v_fma_f32 v37, v154, v37, v157
	v_cvt_pk_bf16_f32 v38, v38, v39
	v_cvt_pk_bf16_f32 v39, v40, v41
	v_cvt_pk_bf16_f32 v40, v34, v35
	v_cvt_pk_bf16_f32 v41, v36, v37
	global_store_dwordx4 v149, v[38:41], s[62:63]
	s_waitcnt lgkmcnt(0)
	v_cvt_f32_ubyte0_e32 v152, v136
	v_cvt_f32_ubyte0_e32 v153, v160
	v_cvt_f32_ubyte0_e32 v154, v162
	v_lshlrev_b32_e32 v155, 16, v172
	v_lshlrev_b32_e32 v156, 16, v176
	v_mul_f32_e32 v152, 0x3b808081, v152
	v_mul_f32_e32 v153, 0x3b808081, v153
	v_mul_f32_e32 v154, 0x3b808081, v154
	v_mul_f32_e32 v157, v152, v155
	v_fmac_f32_e32 v157, v153, v156
	v_fma_f32 v14, v154, v14, v157
	v_cvt_f32_ubyte1_e32 v152, v136
	v_cvt_f32_ubyte1_e32 v153, v160
	v_cvt_f32_ubyte1_e32 v154, v162
	v_and_b32_e32 v155, 0xffff0000, v172
	v_and_b32_e32 v156, 0xffff0000, v176
	v_mul_f32_e32 v152, 0x3b808081, v152
	v_mul_f32_e32 v153, 0x3b808081, v153
	v_mul_f32_e32 v154, 0x3b808081, v154
	v_mul_f32_e32 v157, v152, v155
	v_fmac_f32_e32 v157, v153, v156
	v_fma_f32 v15, v154, v15, v157
	v_cvt_f32_ubyte2_e32 v152, v136
	v_cvt_f32_ubyte2_e32 v153, v160
	v_cvt_f32_ubyte2_e32 v154, v162
	v_lshlrev_b32_e32 v155, 16, v173
	v_lshlrev_b32_e32 v156, 16, v177
	v_mul_f32_e32 v152, 0x3b808081, v152
	v_mul_f32_e32 v153, 0x3b808081, v153
	v_mul_f32_e32 v154, 0x3b808081, v154
	v_mul_f32_e32 v157, v152, v155
	v_fmac_f32_e32 v157, v153, v156
	v_fma_f32 v16, v154, v16, v157
	v_cvt_f32_ubyte3_e32 v152, v136
	v_cvt_f32_ubyte3_e32 v153, v160
	v_cvt_f32_ubyte3_e32 v154, v162
	v_and_b32_e32 v155, 0xffff0000, v173
	v_and_b32_e32 v156, 0xffff0000, v177
	v_mul_f32_e32 v152, 0x3b808081, v152
	v_mul_f32_e32 v153, 0x3b808081, v153
	v_mul_f32_e32 v154, 0x3b808081, v154
	v_mul_f32_e32 v157, v152, v155
	v_fmac_f32_e32 v157, v153, v156
	v_fma_f32 v17, v154, v17, v157
	v_cvt_f32_ubyte0_e32 v152, v137
	v_cvt_f32_ubyte0_e32 v153, v161
	v_cvt_f32_ubyte0_e32 v154, v163
	v_lshlrev_b32_e32 v155, 16, v174
	v_lshlrev_b32_e32 v156, 16, v178
	v_mul_f32_e32 v152, 0x3b808081, v152
	v_mul_f32_e32 v153, 0x3b808081, v153
	v_mul_f32_e32 v154, 0x3b808081, v154
	v_mul_f32_e32 v157, v152, v155
	v_fmac_f32_e32 v157, v153, v156
	v_fma_f32 v10, v154, v10, v157
	v_cvt_f32_ubyte1_e32 v152, v137
	v_cvt_f32_ubyte1_e32 v153, v161
	v_cvt_f32_ubyte1_e32 v154, v163
	v_and_b32_e32 v155, 0xffff0000, v174
	v_and_b32_e32 v156, 0xffff0000, v178
	v_mul_f32_e32 v152, 0x3b808081, v152
	v_mul_f32_e32 v153, 0x3b808081, v153
	v_mul_f32_e32 v154, 0x3b808081, v154
	v_mul_f32_e32 v157, v152, v155
	v_fmac_f32_e32 v157, v153, v156
	v_fma_f32 v11, v154, v11, v157
	v_cvt_f32_ubyte2_e32 v152, v137
	v_cvt_f32_ubyte2_e32 v153, v161
	v_cvt_f32_ubyte2_e32 v154, v163
	v_lshlrev_b32_e32 v155, 16, v175
	v_lshlrev_b32_e32 v156, 16, v179
	v_mul_f32_e32 v152, 0x3b808081, v152
	v_mul_f32_e32 v153, 0x3b808081, v153
	v_mul_f32_e32 v154, 0x3b808081, v154
	v_mul_f32_e32 v157, v152, v155
	v_fmac_f32_e32 v157, v153, v156
	v_fma_f32 v12, v154, v12, v157
	v_cvt_f32_ubyte3_e32 v152, v137
	v_cvt_f32_ubyte3_e32 v153, v161
	v_cvt_f32_ubyte3_e32 v154, v163
	v_and_b32_e32 v155, 0xffff0000, v175
	v_and_b32_e32 v156, 0xffff0000, v179
	v_mul_f32_e32 v152, 0x3b808081, v152
	v_mul_f32_e32 v153, 0x3b808081, v153
	v_mul_f32_e32 v154, 0x3b808081, v154
	v_mul_f32_e32 v157, v152, v155
	v_fmac_f32_e32 v157, v153, v156
	v_fma_f32 v13, v154, v13, v157
	v_cvt_pk_bf16_f32 v14, v14, v15
	v_cvt_pk_bf16_f32 v15, v16, v17
	v_cvt_pk_bf16_f32 v16, v10, v11
	v_cvt_pk_bf16_f32 v17, v12, v13
	global_store_dwordx4 v149, v[14:17], s[62:63] offset:256
	ds_write_b128 v251, v[22:25]
	ds_read_b128 v[22:25], v252
	ds_write_b128 v251, v[18:21]
	ds_read_b128 v[18:21], v252
	ds_write_b128 v251, v[6:9]
	ds_read_b128 v[6:9], v252
	ds_write_b128 v251, v[2:5]
	ds_read_b128 v[2:5], v252
	v_add_u32_e32 v149, 0xb0000, v151
	s_waitcnt vmcnt(2)
; __device__ __forceinline__ void unpack8(const u32x4 w, float* f) { f[0] = bflo(w.x); f[1] = bfhi(w.x); f[2] = bflo(w.y); f[3] = bfhi(w.y); f[4] = bflo(w.z); f[5] = bfhi(w.z); f[6] = bflo(w.w); f[7] = bfhi(w.w); }
; __device__ __forceinline__ u32x4 pack8(const float* f) { u32x4 w; w.x = cvt_pk(f[0], f[1]); w.y = cvt_pk(f[2], f[3]); w.z = cvt_pk(f[4], f[5]); w.w = cvt_pk(f[6], f[7]); return w; }
;     __device__ __forceinline__ void operator()(const f32x4 (&acc)[2][2][4][2], const UnitD& u, int wr, int wc, int fr, int fq) const {
;     ...
;             for (int ai = 0; ai < 2; ++ai)
; #pragma unroll
;                 for (int m = 0; m < 4; ++m) { const int row = row0 + ai * HALF + m * 16;
;                     const unsigned char* gp = (const unsigned char*)(proj + (size_t)row * NP + C_G) + col0; const size_t po = (size_t)row * 2048 + col0;
;                     u32x2 g0[2], g1[2], g2[2]; u32x4 a[2], b[2];
; #pragma unroll
;                     for (int bj = 0; bj < 2; ++bj) { g0[bj] = *(const u32x2*)(gp + bj * HALF); g1[bj] = *(const u32x2*)(gp + 2048 + bj * HALF); g2[bj] = *(const u32x2*)(gp + 4096 + bj * HALF);
;                         a[bj] = *(const u32x4*)(PA + po + bj * HALF); b[bj] = *(const u32x4*)(PB + po + bj * HALF); }
; #pragma unroll
;                     for (int bj = 0; bj < 2; ++bj) { float f0[8], f1[8], f2[8], fa[8], fb[8], o[8];
;                         unpack_u8(g0[bj], f0); unpack_u8(g1[bj], f1); unpack_u8(g2[bj], f2); unpack8(a[bj], fa); unpack8(b[bj], fb);
;                         const f32x4 v0 = acc[ai][bj][m][0], v1 = acc[ai][bj][m][1];
; #pragma unroll
;                         for (int j = 0; j < 4; ++j) { o[j] = f0[j] * fa[j] + f1[j] * fb[j] + f2[j] * v0[j]; o[4 + j] = f0[4 + j] * fa[4 + j] + f1[4 + j] * fb[4 + j] + f2[4 + j] * v1[j]; }
;                         *(u32x4*)(H + po + bj * HALF) = pack8(o); } }
	s_waitcnt lgkmcnt(4)
	v_cvt_f32_ubyte0_e32 v152, v198
	v_cvt_f32_ubyte0_e32 v153, v200
	v_cvt_f32_ubyte0_e32 v154, v202
	v_lshlrev_b32_e32 v155, 16, v210
	v_lshlrev_b32_e32 v156, 16, v214
	v_mul_f32_e32 v152, 0x3b808081, v152
	v_mul_f32_e32 v153, 0x3b808081, v153
	v_mul_f32_e32 v154, 0x3b808081, v154
	v_mul_f32_e32 v157, v152, v155
	v_fmac_f32_e32 v157, v153, v156
	v_fma_f32 v22, v154, v22, v157
	v_cvt_f32_ubyte1_e32 v152, v198
	v_cvt_f32_ubyte1_e32 v153, v200
	v_cvt_f32_ubyte1_e32 v154, v202
	v_and_b32_e32 v155, 0xffff0000, v210
	v_and_b32_e32 v156, 0xffff0000, v214
	v_mul_f32_e32 v152, 0x3b808081, v152
	v_mul_f32_e32 v153, 0x3b808081, v153
	v_mul_f32_e32 v154, 0x3b808081, v154
	v_mul_f32_e32 v157, v152, v155
	v_fmac_f32_e32 v157, v153, v156
	v_fma_f32 v23, v154, v23, v157
	v_cvt_f32_ubyte2_e32 v152, v198
	v_cvt_f32_ubyte2_e32 v153, v200
	v_cvt_f32_ubyte2_e32 v154, v202
	v_lshlrev_b32_e32 v155, 16, v211
	v_lshlrev_b32_e32 v156, 16, v215
	v_mul_f32_e32 v152, 0x3b808081, v152
	v_mul_f32_e32 v153, 0x3b808081, v153
	v_mul_f32_e32 v154, 0x3b808081, v154
	v_mul_f32_e32 v157, v152, v155
	v_fmac_f32_e32 v157, v153, v156
	v_fma_f32 v24, v154, v24, v157
	v_cvt_f32_ubyte3_e32 v152, v198
	v_cvt_f32_ubyte3_e32 v153, v200
	v_cvt_f32_ubyte3_e32 v154, v202
	v_and_b32_e32 v155, 0xffff0000, v211
	v_and_b32_e32 v156, 0xffff0000, v215
	v_mul_f32_e32 v152, 0x3b808081, v152
	v_mul_f32_e32 v153, 0x3b808081, v153
	v_mul_f32_e32 v154, 0x3b808081, v154
	v_mul_f32_e32 v157, v152, v155
	v_fmac_f32_e32 v157, v153, v156
	v_fma_f32 v25, v154, v25, v157
	v_cvt_f32_ubyte0_e32 v152, v199
	v_cvt_f32_ubyte0_e32 v153, v201
	v_cvt_f32_ubyte0_e32 v154, v203
	v_lshlrev_b32_e32 v155, 16, v212
	v_lshlrev_b32_e32 v156, 16, v216
	v_mul_f32_e32 v152, 0x3b808081, v152
	v_mul_f32_e32 v153, 0x3b808081, v153
	v_mul_f32_e32 v154, 0x3b808081, v154
	v_mul_f32_e32 v157, v152, v155
	v_fmac_f32_e32 v157, v153, v156
	v_fma_f32 v18, v154, v18, v157
	v_cvt_f32_ubyte1_e32 v152, v199
	v_cvt_f32_ubyte1_e32 v153, v201
	v_cvt_f32_ubyte1_e32 v154, v203
	v_and_b32_e32 v155, 0xffff0000, v212
	v_and_b32_e32 v156, 0xffff0000, v216
	v_mul_f32_e32 v152, 0x3b808081, v152
	v_mul_f32_e32 v153, 0x3b808081, v153
	v_mul_f32_e32 v154, 0x3b808081, v154
	v_mul_f32_e32 v157, v152, v155
	v_fmac_f32_e32 v157, v153, v156
	v_fma_f32 v19, v154, v19, v157
	v_cvt_f32_ubyte2_e32 v152, v199
	v_cvt_f32_ubyte2_e32 v153, v201
	v_cvt_f32_ubyte2_e32 v154, v203
	v_lshlrev_b32_e32 v155, 16, v213
	v_lshlrev_b32_e32 v156, 16, v217
	v_mul_f32_e32 v152, 0x3b808081, v152
	v_mul_f32_e32 v153, 0x3b808081, v153
	v_mul_f32_e32 v154, 0x3b808081, v154
	v_mul_f32_e32 v157, v152, v155
	v_fmac_f32_e32 v157, v153, v156
	v_fma_f32 v20, v154, v20, v157
	v_cvt_f32_ubyte3_e32 v152, v199
	v_cvt_f32_ubyte3_e32 v153, v201
	v_cvt_f32_ubyte3_e32 v154, v203
	v_and_b32_e32 v155, 0xffff0000, v213
	v_and_b32_e32 v156, 0xffff0000, v217
	v_mul_f32_e32 v152, 0x3b808081, v152
	v_mul_f32_e32 v153, 0x3b808081, v153
	v_mul_f32_e32 v154, 0x3b808081, v154
	v_mul_f32_e32 v157, v152, v155
	v_fmac_f32_e32 v157, v153, v156
	v_fma_f32 v21, v154, v21, v157
	v_cvt_pk_bf16_f32 v22, v22, v23
	v_cvt_pk_bf16_f32 v23, v24, v25
	v_cvt_pk_bf16_f32 v24, v18, v19
	v_cvt_pk_bf16_f32 v25, v20, v21
	global_store_dwordx4 v149, v[22:25], s[62:63]
	s_waitcnt lgkmcnt(0)
	v_cvt_f32_ubyte0_e32 v152, v204
	v_cvt_f32_ubyte0_e32 v153, v206
	v_cvt_f32_ubyte0_e32 v154, v208
	v_lshlrev_b32_e32 v155, 16, v218
	v_lshlrev_b32_e32 v156, 16, v222
	v_mul_f32_e32 v152, 0x3b808081, v152
	v_mul_f32_e32 v153, 0x3b808081, v153
	v_mul_f32_e32 v154, 0x3b808081, v154
	v_mul_f32_e32 v157, v152, v155
	v_fmac_f32_e32 v157, v153, v156
	v_fma_f32 v6, v154, v6, v157
	v_cvt_f32_ubyte1_e32 v152, v204
	v_cvt_f32_ubyte1_e32 v153, v206
	v_cvt_f32_ubyte1_e32 v154, v208
	v_and_b32_e32 v155, 0xffff0000, v218
	v_and_b32_e32 v156, 0xffff0000, v222
	v_mul_f32_e32 v152, 0x3b808081, v152
	v_mul_f32_e32 v153, 0x3b808081, v153
	v_mul_f32_e32 v154, 0x3b808081, v154
	v_mul_f32_e32 v157, v152, v155
	v_fmac_f32_e32 v157, v153, v156
	v_fma_f32 v7, v154, v7, v157
	v_cvt_f32_ubyte2_e32 v152, v204
	v_cvt_f32_ubyte2_e32 v153, v206
	v_cvt_f32_ubyte2_e32 v154, v208
	v_lshlrev_b32_e32 v155, 16, v219
	v_lshlrev_b32_e32 v156, 16, v223
	v_mul_f32_e32 v152, 0x3b808081, v152
	v_mul_f32_e32 v153, 0x3b808081, v153
	v_mul_f32_e32 v154, 0x3b808081, v154
	v_mul_f32_e32 v157, v152, v155
	v_fmac_f32_e32 v157, v153, v156
	v_fma_f32 v8, v154, v8, v157
	v_cvt_f32_ubyte3_e32 v152, v204
	v_cvt_f32_ubyte3_e32 v153, v206
	v_cvt_f32_ubyte3_e32 v154, v208
	v_and_b32_e32 v155, 0xffff0000, v219
	v_and_b32_e32 v156, 0xffff0000, v223
	v_mul_f32_e32 v152, 0x3b808081, v152
	v_mul_f32_e32 v153, 0x3b808081, v153
	v_mul_f32_e32 v154, 0x3b808081, v154
	v_mul_f32_e32 v157, v152, v155
	v_fmac_f32_e32 v157, v153, v156
	v_fma_f32 v9, v154, v9, v157
	v_cvt_f32_ubyte0_e32 v152, v205
	v_cvt_f32_ubyte0_e32 v153, v207
	v_cvt_f32_ubyte0_e32 v154, v209
	v_lshlrev_b32_e32 v155, 16, v220
	v_lshlrev_b32_e32 v156, 16, v224
	v_mul_f32_e32 v152, 0x3b808081, v152
	v_mul_f32_e32 v153, 0x3b808081, v153
	v_mul_f32_e32 v154, 0x3b808081, v154
	v_mul_f32_e32 v157, v152, v155
	v_fmac_f32_e32 v157, v153, v156
	v_fma_f32 v2, v154, v2, v157
	v_cvt_f32_ubyte1_e32 v152, v205
	v_cvt_f32_ubyte1_e32 v153, v207
	v_cvt_f32_ubyte1_e32 v154, v209
	v_and_b32_e32 v155, 0xffff0000, v220
	v_and_b32_e32 v156, 0xffff0000, v224
	v_mul_f32_e32 v152, 0x3b808081, v152
	v_mul_f32_e32 v153, 0x3b808081, v153
	v_mul_f32_e32 v154, 0x3b808081, v154
	v_mul_f32_e32 v157, v152, v155
	v_fmac_f32_e32 v157, v153, v156
	v_fma_f32 v3, v154, v3, v157
	v_cvt_f32_ubyte2_e32 v152, v205
	v_cvt_f32_ubyte2_e32 v153, v207
	v_cvt_f32_ubyte2_e32 v154, v209
	v_lshlrev_b32_e32 v155, 16, v221
	v_lshlrev_b32_e32 v156, 16, v225
	v_mul_f32_e32 v152, 0x3b808081, v152
	v_mul_f32_e32 v153, 0x3b808081, v153
	v_mul_f32_e32 v154, 0x3b808081, v154
	v_mul_f32_e32 v157, v152, v155
	v_fmac_f32_e32 v157, v153, v156
	v_fma_f32 v4, v154, v4, v157
	v_cvt_f32_ubyte3_e32 v152, v205
	v_cvt_f32_ubyte3_e32 v153, v207
	v_cvt_f32_ubyte3_e32 v154, v209
	v_and_b32_e32 v155, 0xffff0000, v221
	v_and_b32_e32 v156, 0xffff0000, v225
	v_mul_f32_e32 v152, 0x3b808081, v152
	v_mul_f32_e32 v153, 0x3b808081, v153
	v_mul_f32_e32 v154, 0x3b808081, v154
	v_mul_f32_e32 v157, v152, v155
	v_fmac_f32_e32 v157, v153, v156
	v_fma_f32 v5, v154, v5, v157
	v_cvt_pk_bf16_f32 v6, v6, v7
	v_cvt_pk_bf16_f32 v7, v8, v9
	v_cvt_pk_bf16_f32 v8, v2, v3
	v_cvt_pk_bf16_f32 v9, v4, v5
	global_store_dwordx4 v149, v[6:9], s[62:63] offset:256
	s_branch .Lg3_done
; __device__ __forceinline__ unsigned cvt_pk(float lo, float hi) { unsigned r; asm volatile("v_cvt_pk_bf16_f32 %0, %1, %2" : "=v"(r) : "v"(lo), "v"(hi)); return r; }
; #define GAS __attribute__((address_space(1)))
;     __device__ __forceinline__ void operator()(const f32x4 (&acc)[2][2][4][2], const UnitD& u, int wr, int wc, int fr, int fq) const {
;     ...
;         if (u.kind < 2) {
;             GAS bf16_t* C = (GAS bf16_t*)(unsigned long long)u.C;
; #pragma unroll
;             for (int ai = 0; ai < 2; ++ai)
; #pragma unroll
;                 for (int m = 0; m < 4; ++m) { GAS bf16_t* rowp = C + (size_t)(row0 + ai * HALF + m * 16) * 2048 + col0;
; #pragma unroll
;                     for (int bj = 0; bj < 2; ++bj) { const f32x4 v0 = acc[ai][bj][m][0], v1 = acc[ai][bj][m][1];
;                         u32x4 w; w.x = cvt_pk(v0[0], v0[1]); w.y = cvt_pk(v0[2], v0[3]); w.z = cvt_pk(v1[0], v1[1]); w.w = cvt_pk(v1[2], v1[3]);
;                         *(GAS u32x4*)(rowp + bj * HALF) = w; } }
.Lg3_k01:
	v_cvt_pk_bf16_f32 v126, v126, v127
	v_cvt_pk_bf16_f32 v127, v128, v129
	v_cvt_pk_bf16_f32 v128, v122, v123
	v_cvt_pk_bf16_f32 v129, v124, v125
	ds_write_b128 v251, v[126:129]
	ds_read_b128 v[126:129], v252
	v_cvt_pk_bf16_f32 v110, v110, v111
	v_cvt_pk_bf16_f32 v111, v112, v113
	v_cvt_pk_bf16_f32 v112, v106, v107
	v_cvt_pk_bf16_f32 v113, v108, v109
	ds_write_b128 v251, v[110:113]
	ds_read_b128 v[110:113], v252
	v_cvt_pk_bf16_f32 v118, v118, v119
	v_cvt_pk_bf16_f32 v119, v120, v121
	v_cvt_pk_bf16_f32 v120, v114, v115
	v_cvt_pk_bf16_f32 v121, v116, v117
	ds_write_b128 v251, v[118:121]
	ds_read_b128 v[118:121], v252
	v_mov_b32_e32 v253, v145
	s_waitcnt lgkmcnt(4)
	global_store_dwordx4 v253, v[126:129], s[16:17]
	v_cvt_pk_bf16_f32 v94, v94, v95
	v_cvt_pk_bf16_f32 v95, v96, v97
	v_cvt_pk_bf16_f32 v96, v90, v91
	v_cvt_pk_bf16_f32 v97, v92, v93
	ds_write_b128 v251, v[94:97]
	ds_read_b128 v[94:97], v252
	s_waitcnt lgkmcnt(4)
	global_store_dwordx4 v253, v[110:113], s[16:17] offset:256
	v_cvt_pk_bf16_f32 v102, v102, v103
	v_cvt_pk_bf16_f32 v103, v104, v105
	v_cvt_pk_bf16_f32 v104, v98, v99
	v_cvt_pk_bf16_f32 v105, v100, v101
	ds_write_b128 v251, v[102:105]
	ds_read_b128 v[102:105], v252
	v_add_u32_e32 v253, 0x2000, v145
	s_waitcnt lgkmcnt(4)
	global_store_dwordx4 v253, v[118:121], s[16:17]
	v_cvt_pk_bf16_f32 v78, v78, v79
	v_cvt_pk_bf16_f32 v79, v80, v81
	v_cvt_pk_bf16_f32 v80, v74, v75
	v_cvt_pk_bf16_f32 v81, v76, v77
	ds_write_b128 v251, v[78:81]
	ds_read_b128 v[78:81], v252
	s_waitcnt lgkmcnt(4)
	global_store_dwordx4 v253, v[94:97], s[16:17] offset:256
	v_cvt_pk_bf16_f32 v86, v86, v87
	v_cvt_pk_bf16_f32 v87, v88, v89
	v_cvt_pk_bf16_f32 v88, v82, v83
	v_cvt_pk_bf16_f32 v89, v84, v85
	ds_write_b128 v251, v[86:89]
	ds_read_b128 v[86:89], v252
	v_add_u32_e32 v253, 0x4000, v145
	s_waitcnt lgkmcnt(4)
	global_store_dwordx4 v253, v[102:105], s[16:17]
	v_cvt_pk_bf16_f32 v70, v70, v71
	v_cvt_pk_bf16_f32 v71, v72, v73
	v_cvt_pk_bf16_f32 v72, v66, v67
	v_cvt_pk_bf16_f32 v73, v68, v69
	ds_write_b128 v251, v[70:73]
	ds_read_b128 v[70:73], v252
	s_waitcnt lgkmcnt(4)
	global_store_dwordx4 v253, v[78:81], s[16:17] offset:256
	v_cvt_pk_bf16_f32 v62, v62, v63
	v_cvt_pk_bf16_f32 v63, v64, v65
	v_cvt_pk_bf16_f32 v64, v58, v59
	v_cvt_pk_bf16_f32 v65, v60, v61
	ds_write_b128 v251, v[62:65]
	ds_read_b128 v[62:65], v252
	v_add_u32_e32 v253, 0x6000, v145
	s_waitcnt lgkmcnt(4)
	global_store_dwordx4 v253, v[86:89], s[16:17]
	v_cvt_pk_bf16_f32 v46, v46, v47
	v_cvt_pk_bf16_f32 v47, v48, v49
	v_cvt_pk_bf16_f32 v48, v42, v43
	v_cvt_pk_bf16_f32 v49, v44, v45
	ds_write_b128 v251, v[46:49]
	ds_read_b128 v[46:49], v252
	s_waitcnt lgkmcnt(4)
	global_store_dwordx4 v253, v[70:73], s[16:17] offset:256
	v_cvt_pk_bf16_f32 v54, v54, v55
	v_cvt_pk_bf16_f32 v55, v56, v57
	v_cvt_pk_bf16_f32 v56, v50, v51
	v_cvt_pk_bf16_f32 v57, v52, v53
	ds_write_b128 v251, v[54:57]
	ds_read_b128 v[54:57], v252
	v_add_u32_e32 v253, 0x10000, v145
	s_waitcnt lgkmcnt(4)
	global_store_dwordx4 v253, v[62:65], s[16:17]
	v_cvt_pk_bf16_f32 v30, v30, v31
	v_cvt_pk_bf16_f32 v31, v32, v33
	v_cvt_pk_bf16_f32 v32, v26, v27
	v_cvt_pk_bf16_f32 v33, v28, v29
	ds_write_b128 v251, v[30:33]
	ds_read_b128 v[30:33], v252
	s_waitcnt lgkmcnt(4)
	global_store_dwordx4 v253, v[46:49], s[16:17] offset:256
	v_cvt_pk_bf16_f32 v38, v38, v39
	v_cvt_pk_bf16_f32 v39, v40, v41
	v_cvt_pk_bf16_f32 v40, v34, v35
	v_cvt_pk_bf16_f32 v41, v36, v37
	ds_write_b128 v251, v[38:41]
	ds_read_b128 v[38:41], v252
	v_add_u32_e32 v253, 0x12000, v145
	s_waitcnt lgkmcnt(4)
	global_store_dwordx4 v253, v[54:57], s[16:17]
	v_cvt_pk_bf16_f32 v14, v14, v15
	v_cvt_pk_bf16_f32 v15, v16, v17
	v_cvt_pk_bf16_f32 v16, v10, v11
	v_cvt_pk_bf16_f32 v17, v12, v13
	ds_write_b128 v251, v[14:17]
	ds_read_b128 v[14:17], v252
	s_waitcnt lgkmcnt(4)
	global_store_dwordx4 v253, v[30:33], s[16:17] offset:256
	v_cvt_pk_bf16_f32 v22, v22, v23
	v_cvt_pk_bf16_f32 v23, v24, v25
	v_cvt_pk_bf16_f32 v24, v18, v19
	v_cvt_pk_bf16_f32 v25, v20, v21
	ds_write_b128 v251, v[22:25]
	ds_read_b128 v[22:25], v252
	v_add_u32_e32 v253, 0x14000, v145
	s_waitcnt lgkmcnt(4)
	global_store_dwordx4 v253, v[38:41], s[16:17]
	v_cvt_pk_bf16_f32 v6, v6, v7
	v_cvt_pk_bf16_f32 v7, v8, v9
	v_cvt_pk_bf16_f32 v8, v2, v3
	v_cvt_pk_bf16_f32 v9, v4, v5
	ds_write_b128 v251, v[6:9]
	ds_read_b128 v[6:9], v252
	s_waitcnt lgkmcnt(4)
	global_store_dwordx4 v253, v[14:17], s[16:17] offset:256
	v_add_u32_e32 v253, 0x16000, v145
	s_waitcnt lgkmcnt(2)
	global_store_dwordx4 v253, v[22:25], s[16:17]
	s_waitcnt lgkmcnt(0)
	global_store_dwordx4 v253, v[6:9], s[16:17] offset:256
